# cand2 + sc0 (workgroup scope) on the 64 K-loop LDS-DMA loads
# speedup vs baseline: 1.0006x; 1.0006x over previous
; #define PG8_STAGE(bufoff, gbase, voff) do { const char* gb_ = (const char*)(gbase); asm volatile("" : "+s"(gb_)); _Pragma("unroll") for (int _i = 0; _i < 2; ++_i) { unsigned vo_ = (voff)[_i]; asm volatile("" : "+v"(vo_));        \
;         __builtin_amdgcn_global_load_lds((const unsigned*)(gb_ + vo_), (PG8_LAS unsigned*)(lds + (bufoff) + ldsw + _i * 8192), 16, 0, 0); } } while (0)
; #define PG8_LDA(dst, b, h) do { _Pragma("unroll") for (int m = 0; m < 4; ++m) _Pragma("unroll") for (int k = 0; k < 2; ++k) dst[m][k] = *(const PG8_LAS bf16x8*)(lds + PG8_SA(b, h) + aoff + m * 2048 + k * 1024); } while (0)
; #define PG8_LDB(dst, b, h) do { _Pragma("unroll") for (int n = 0; n < 2; ++n) _Pragma("unroll") for (int k = 0; k < 2; ++k) dst[n][k] = *(const PG8_LAS bf16x8*)(lds + PG8_SB(b, h) + boff + n * 2048 + k * 1024); } while (0)
; #define PG8_MMA(ai, bj, At, Bt) do { __builtin_amdgcn_s_setprio(1); _Pragma("unroll") for (int m = 0; m < 4; ++m) _Pragma("unroll") for (int n = 0; n < 2; ++n) _Pragma("unroll") for (int k = 0; k < 2; ++k) \
;         acc[ai][bj][m][n] = __builtin_amdgcn_mfma_f32_16x16x32_bf16(Bt[n][k], At[m][k], acc[ai][bj][m][n], 0, 0, 0); __builtin_amdgcn_s_setprio(0); } while (0)
; #define PG8_WAIT_V(n) asm volatile("s_waitcnt vmcnt(" #n ")" ::: "memory")
; template <class Epi, class Sched, bool ALIGN_EPI = false, bool SP2 = false>
; __device__ __forceinline__ void gemm_phase(PG8_LAS unsigned char* lds, const Gemm g, const Sched& S, const Epi& E) {
;     ...
;             const bool last = (t == nt - 2);
;             const char* a1 = cA + (size_t)(t + 1) * kstep;
;             const char* a2 = last ? nA : cA + (size_t)(t + 2) * kstep; const char* b2 = last ? nB : cB + (size_t)(t + 2) * kstep;
;             const char* a3 = a2 + kstep; const char* b3 = b2 + kstep;
;             if (last && has_next) S.a_ready(nxt);
;             if constexpr (SP2) {
;             PG8_LDB(B0, 0, 0); PG8_LDB(B1, 0, 1); PG8_SCHED; PG8_LDA(At, 0, 0); PG8_STAGE(PG8_SA(1, 1), a1 + hstep, voffA);
;             PG8_WAIT_V(8); PG8_WAIT_L(0); PG8_BAR; PG8_MMA(0, 0, At, B0); PG8_MMA(0, 1, At, B1); PG8_BAR; PG8_SCHED;
;             PG8_LDA(At, 0, 1); PG8_STAGE(PG8_SB(0, 0), b2, voffB); PG8_STAGE(PG8_SB(0, 1), b2 + hstep, voffB); PG8_STAGE(PG8_SA(0, 0), a2, voffA);
;             PG8_WAIT_V(8); PG8_WAIT_L(0); PG8_BAR; PG8_MMA(1, 0, At, B0); PG8_MMA(1, 1, At, B1); PG8_BAR; PG8_SCHED;
.LBB0_232:
	s_add_u32 s2, s0, 0x100
	s_addc_u32 s3, s1, 0
	s_cmp_eq_u32 s30, 28
	s_cselect_b32 s10, s25, s2
	s_cselect_b32 s11, s24, s3
	s_cselect_b32 s8, s27, s28
	s_cselect_b32 s9, s26, s29
	s_add_u32 s6, s10, 0x80
	s_addc_u32 s7, s11, 0
	s_add_i32 s31, 0, 0x10000
	s_add_i32 s33, 0, 0x14000
	ds_read_b128 v[66:69], v244
	ds_read_b128 v[70:73], v244 offset:1024
	ds_read_b128 v[74:77], v244 offset:2048
	ds_read_b128 v[78:81], v244 offset:3072
	ds_read_b128 v[146:149], v244 offset:16384
	ds_read_b128 v[150:153], v244 offset:17408
	ds_read_b128 v[154:157], v244 offset:18432
	ds_read_b128 v[158:161], v244 offset:19456
	s_add_u32 s0, s0, 0x80080
	s_addc_u32 s1, s1, 0
	ds_read_b128 v[178:181], v223
	ds_read_b128 v[182:185], v223 offset:1024
	ds_read_b128 v[192:195], v223 offset:2048
	ds_read_b128 v[196:199], v223 offset:3072
	ds_read_b128 v[200:203], v223 offset:4096
	ds_read_b128 v[204:207], v223 offset:5120
	ds_read_b128 v[208:211], v223 offset:6144
	ds_read_b128 v[212:215], v223 offset:7168
	s_add_i32 m0, s13, 0xc000
	s_nop 0
	global_load_lds_dwordx4 v1, s[0:1] sc0
	s_add_i32 m0, s13, 0xe000
	s_nop 0
	global_load_lds_dwordx4 v191, s[0:1] sc0
	s_waitcnt vmcnt(8)
	s_waitcnt lgkmcnt(0)
	s_barrier
	s_setprio 1
	s_waitcnt lgkmcnt(0)
	v_mfma_f32_16x16x32_bf16 v[142:145], v[66:69], v[178:181], v[142:145]
	v_mfma_f32_16x16x32_bf16 v[142:145], v[70:73], v[182:185], v[142:145]
	v_mfma_f32_16x16x32_bf16 v[134:137], v[66:69], v[192:195], v[134:137]
	v_mfma_f32_16x16x32_bf16 v[134:137], v[70:73], v[196:199], v[134:137]
	v_mfma_f32_16x16x32_bf16 v[126:129], v[66:69], v[200:203], v[126:129]
	v_mfma_f32_16x16x32_bf16 v[126:129], v[70:73], v[204:207], v[126:129]
	v_mfma_f32_16x16x32_bf16 v[118:121], v[66:69], v[208:211], v[118:121]
	v_mfma_f32_16x16x32_bf16 v[118:121], v[70:73], v[212:215], v[118:121]
	v_mfma_f32_16x16x32_bf16 v[138:141], v[74:77], v[178:181], v[138:141]
	v_mfma_f32_16x16x32_bf16 v[138:141], v[78:81], v[182:185], v[138:141]
	v_mfma_f32_16x16x32_bf16 v[130:133], v[74:77], v[192:195], v[130:133]
	v_mfma_f32_16x16x32_bf16 v[130:133], v[78:81], v[196:199], v[130:133]
	v_mfma_f32_16x16x32_bf16 v[122:125], v[74:77], v[200:203], v[122:125]
	v_mfma_f32_16x16x32_bf16 v[122:125], v[78:81], v[204:207], v[122:125]
	v_mfma_f32_16x16x32_bf16 v[114:117], v[74:77], v[208:211], v[114:117]
	v_mfma_f32_16x16x32_bf16 v[114:117], v[78:81], v[212:215], v[114:117]
	s_setprio 0
	s_setprio 1
	v_mfma_f32_16x16x32_bf16 v[62:65], v[146:149], v[178:181], v[62:65]
	v_mfma_f32_16x16x32_bf16 v[62:65], v[150:153], v[182:185], v[62:65]
	v_mfma_f32_16x16x32_bf16 v[54:57], v[146:149], v[192:195], v[54:57]
	v_mfma_f32_16x16x32_bf16 v[54:57], v[150:153], v[196:199], v[54:57]
	v_mfma_f32_16x16x32_bf16 v[46:49], v[146:149], v[200:203], v[46:49]
	v_mfma_f32_16x16x32_bf16 v[46:49], v[150:153], v[204:207], v[46:49]
	v_mfma_f32_16x16x32_bf16 v[38:41], v[146:149], v[208:211], v[38:41]
	v_mfma_f32_16x16x32_bf16 v[38:41], v[150:153], v[212:215], v[38:41]
	v_mfma_f32_16x16x32_bf16 v[58:61], v[154:157], v[178:181], v[58:61]
	v_mfma_f32_16x16x32_bf16 v[58:61], v[158:161], v[182:185], v[58:61]
	v_mfma_f32_16x16x32_bf16 v[50:53], v[154:157], v[192:195], v[50:53]
	v_mfma_f32_16x16x32_bf16 v[50:53], v[158:161], v[196:199], v[50:53]
	v_mfma_f32_16x16x32_bf16 v[42:45], v[154:157], v[200:203], v[42:45]
	v_mfma_f32_16x16x32_bf16 v[42:45], v[158:161], v[204:207], v[42:45]
	v_mfma_f32_16x16x32_bf16 v[34:37], v[154:157], v[208:211], v[34:37]
	v_mfma_f32_16x16x32_bf16 v[34:37], v[158:161], v[212:215], v[34:37]
	s_setprio 0
	s_barrier
	s_mov_b64 s[0:1], s[8:9]
	s_add_i32 s31, s31, s12
	ds_read_b128 v[178:181], v223 offset:16384
	ds_read_b128 v[182:185], v223 offset:17408
	ds_read_b128 v[192:195], v223 offset:18432
	ds_read_b128 v[196:199], v223 offset:19456
	ds_read_b128 v[200:203], v223 offset:20480
	ds_read_b128 v[204:207], v223 offset:21504
	ds_read_b128 v[208:211], v223 offset:22528
	ds_read_b128 v[212:215], v223 offset:23552
	s_mov_b32 m0, s31
	s_nop 0
	global_load_lds_dwordx4 v189, s[0:1] sc0
	s_add_i32 m0, s31, 0x2000
	s_nop 0
	global_load_lds_dwordx4 v219, s[0:1] sc0
	s_add_u32 s0, s8, 0x80000
	s_addc_u32 s1, s9, 0
	s_add_i32 s31, s33, s12
	s_mov_b32 m0, s31
	s_nop 0
	global_load_lds_dwordx4 v189, s[0:1] sc0
	s_add_i32 m0, s31, 0x2000
	s_nop 0
	global_load_lds_dwordx4 v219, s[0:1] sc0
	s_mov_b64 s[0:1], s[10:11]
	s_mov_b32 m0, s13
	s_nop 0
	global_load_lds_dwordx4 v1, s[0:1] sc0
	s_mov_b32 m0, s14
	s_nop 0
	global_load_lds_dwordx4 v191, s[0:1] sc0
	s_waitcnt vmcnt(8)
	s_waitcnt lgkmcnt(0)
	s_barrier
; #define PG8_STAGE(bufoff, gbase, voff) do { const char* gb_ = (const char*)(gbase); asm volatile("" : "+s"(gb_)); _Pragma("unroll") for (int _i = 0; _i < 2; ++_i) { unsigned vo_ = (voff)[_i]; asm volatile("" : "+v"(vo_));        \
;         __builtin_amdgcn_global_load_lds((const unsigned*)(gb_ + vo_), (PG8_LAS unsigned*)(lds + (bufoff) + ldsw + _i * 8192), 16, 0, 0); } } while (0)
; #define PG8_LDA(dst, b, h) do { _Pragma("unroll") for (int m = 0; m < 4; ++m) _Pragma("unroll") for (int k = 0; k < 2; ++k) dst[m][k] = *(const PG8_LAS bf16x8*)(lds + PG8_SA(b, h) + aoff + m * 2048 + k * 1024); } while (0)
; #define PG8_LDB(dst, b, h) do { _Pragma("unroll") for (int n = 0; n < 2; ++n) _Pragma("unroll") for (int k = 0; k < 2; ++k) dst[n][k] = *(const PG8_LAS bf16x8*)(lds + PG8_SB(b, h) + boff + n * 2048 + k * 1024); } while (0)
; #define PG8_MMA(ai, bj, At, Bt) do { __builtin_amdgcn_s_setprio(1); _Pragma("unroll") for (int m = 0; m < 4; ++m) _Pragma("unroll") for (int n = 0; n < 2; ++n) _Pragma("unroll") for (int k = 0; k < 2; ++k) \
;         acc[ai][bj][m][n] = __builtin_amdgcn_mfma_f32_16x16x32_bf16(Bt[n][k], At[m][k], acc[ai][bj][m][n], 0, 0, 0); __builtin_amdgcn_s_setprio(0); } while (0)
; #define PG8_WAIT_V(n) asm volatile("s_waitcnt vmcnt(" #n ")" ::: "memory")
; #define PG8_WAIT_L(n) asm volatile("s_waitcnt lgkmcnt(" #n ")" ::: "memory")
; #define PG8_BAR __builtin_amdgcn_s_barrier()
; #define PG8_SCHED __builtin_amdgcn_sched_barrier(0)
; template <class Epi, class Sched, bool ALIGN_EPI = false, bool SP2 = false>
; __device__ __forceinline__ void gemm_phase(PG8_LAS unsigned char* lds, const Gemm g, const Sched& S, const Epi& E) {
;     ...
;             PG8_WAIT_V(8); PG8_WAIT_L(0); PG8_BAR; PG8_MMA(1, 0, At, B0); PG8_MMA(1, 1, At, B1); PG8_BAR; PG8_SCHED;
;             PG8_LDB(B0, 1, 0); PG8_LDB(B1, 1, 1); PG8_SCHED; PG8_LDA(At, 1, 0); PG8_STAGE(PG8_SA(0, 1), a2 + hstep, voffA);
;             PG8_WAIT_V(8); PG8_WAIT_L(0); PG8_BAR; PG8_MMA(0, 0, At, B0); PG8_MMA(0, 1, At, B1); PG8_BAR; PG8_SCHED;
	s_setprio 1
	s_waitcnt lgkmcnt(0)
	v_mfma_f32_16x16x32_bf16 v[110:113], v[66:69], v[178:181], v[110:113]
	v_mfma_f32_16x16x32_bf16 v[110:113], v[70:73], v[182:185], v[110:113]
	v_mfma_f32_16x16x32_bf16 v[102:105], v[66:69], v[192:195], v[102:105]
	v_mfma_f32_16x16x32_bf16 v[102:105], v[70:73], v[196:199], v[102:105]
	v_mfma_f32_16x16x32_bf16 v[94:97], v[66:69], v[200:203], v[94:97]
	v_mfma_f32_16x16x32_bf16 v[94:97], v[70:73], v[204:207], v[94:97]
	v_mfma_f32_16x16x32_bf16 v[66:69], v[66:69], v[208:211], v[86:89]
	v_mfma_f32_16x16x32_bf16 v[66:69], v[70:73], v[212:215], v[66:69]
	v_mfma_f32_16x16x32_bf16 v[106:109], v[74:77], v[178:181], v[106:109]
	v_mfma_f32_16x16x32_bf16 v[106:109], v[78:81], v[182:185], v[106:109]
	v_mfma_f32_16x16x32_bf16 v[98:101], v[74:77], v[192:195], v[98:101]
	v_mfma_f32_16x16x32_bf16 v[98:101], v[78:81], v[196:199], v[98:101]
	v_mfma_f32_16x16x32_bf16 v[90:93], v[74:77], v[200:203], v[90:93]
	v_mfma_f32_16x16x32_bf16 v[90:93], v[78:81], v[204:207], v[90:93]
	v_mfma_f32_16x16x32_bf16 v[70:73], v[74:77], v[208:211], v[82:85]
	v_mfma_f32_16x16x32_bf16 v[70:73], v[78:81], v[212:215], v[70:73]
	s_setprio 0
	s_setprio 1
	v_mfma_f32_16x16x32_bf16 v[30:33], v[146:149], v[178:181], v[30:33]
	v_mfma_f32_16x16x32_bf16 v[30:33], v[150:153], v[182:185], v[30:33]
	v_mfma_f32_16x16x32_bf16 v[22:25], v[146:149], v[192:195], v[22:25]
	v_mfma_f32_16x16x32_bf16 v[22:25], v[150:153], v[196:199], v[22:25]
	v_mfma_f32_16x16x32_bf16 v[14:17], v[146:149], v[200:203], v[14:17]
	v_mfma_f32_16x16x32_bf16 v[14:17], v[150:153], v[204:207], v[14:17]
	v_mfma_f32_16x16x32_bf16 v[6:9], v[146:149], v[208:211], v[6:9]
	v_mfma_f32_16x16x32_bf16 v[6:9], v[150:153], v[212:215], v[6:9]
	v_mfma_f32_16x16x32_bf16 v[26:29], v[154:157], v[178:181], v[26:29]
	v_mfma_f32_16x16x32_bf16 v[26:29], v[158:161], v[182:185], v[26:29]
	v_mfma_f32_16x16x32_bf16 v[18:21], v[154:157], v[192:195], v[18:21]
	v_mfma_f32_16x16x32_bf16 v[18:21], v[158:161], v[196:199], v[18:21]
	v_mfma_f32_16x16x32_bf16 v[10:13], v[154:157], v[200:203], v[10:13]
	v_mfma_f32_16x16x32_bf16 v[10:13], v[158:161], v[204:207], v[10:13]
	v_mfma_f32_16x16x32_bf16 v[2:5], v[154:157], v[208:211], v[2:5]
	v_mfma_f32_16x16x32_bf16 v[2:5], v[158:161], v[212:215], v[2:5]
	s_setprio 0
	s_barrier
	s_add_i32 s31, 0, 0x18000
	s_add_i32 s33, 0, 0x1c000
	ds_read_b128 v[74:77], v244 offset:32768
	ds_read_b128 v[78:81], v244 offset:33792
	ds_read_b128 v[82:85], v244 offset:34816
	ds_read_b128 v[146:149], v244 offset:35840
	ds_read_b128 v[150:153], v244 offset:49152
	ds_read_b128 v[154:157], v244 offset:50176
	ds_read_b128 v[158:161], v244 offset:51200
	ds_read_b128 v[178:181], v244 offset:52224
	s_add_u32 s0, s10, 0x80000
	s_addc_u32 s1, s11, 0
	s_mov_b32 m0, s15
	ds_read_b128 v[86:89], v223 offset:32768
	ds_read_b128 v[182:185], v223 offset:33792
	ds_read_b128 v[192:195], v223 offset:34816
	ds_read_b128 v[196:199], v223 offset:35840
	ds_read_b128 v[200:203], v223 offset:36864
	ds_read_b128 v[204:207], v223 offset:37888
	ds_read_b128 v[208:211], v223 offset:38912
	ds_read_b128 v[212:215], v223 offset:39936
	s_nop 0
	global_load_lds_dwordx4 v1, s[0:1] sc0
	s_mov_b32 m0, s16
	s_nop 0
	global_load_lds_dwordx4 v191, s[0:1] sc0
	s_waitcnt vmcnt(8)
	s_waitcnt lgkmcnt(0)
	s_barrier
	s_setprio 1
	s_waitcnt lgkmcnt(0)
	v_mfma_f32_16x16x32_bf16 v[142:145], v[74:77], v[86:89], v[142:145]
	v_mfma_f32_16x16x32_bf16 v[142:145], v[78:81], v[182:185], v[142:145]
	v_mfma_f32_16x16x32_bf16 v[134:137], v[74:77], v[192:195], v[134:137]
	v_mfma_f32_16x16x32_bf16 v[134:137], v[78:81], v[196:199], v[134:137]
	v_mfma_f32_16x16x32_bf16 v[126:129], v[74:77], v[200:203], v[126:129]
	v_mfma_f32_16x16x32_bf16 v[126:129], v[78:81], v[204:207], v[126:129]
	v_mfma_f32_16x16x32_bf16 v[118:121], v[74:77], v[208:211], v[118:121]
	v_mfma_f32_16x16x32_bf16 v[118:121], v[78:81], v[212:215], v[118:121]
	v_mfma_f32_16x16x32_bf16 v[138:141], v[82:85], v[86:89], v[138:141]
	v_mfma_f32_16x16x32_bf16 v[138:141], v[146:149], v[182:185], v[138:141]
	v_mfma_f32_16x16x32_bf16 v[130:133], v[82:85], v[192:195], v[130:133]
	v_mfma_f32_16x16x32_bf16 v[130:133], v[146:149], v[196:199], v[130:133]
	v_mfma_f32_16x16x32_bf16 v[122:125], v[82:85], v[200:203], v[122:125]
	v_mfma_f32_16x16x32_bf16 v[122:125], v[146:149], v[204:207], v[122:125]
	v_mfma_f32_16x16x32_bf16 v[114:117], v[82:85], v[208:211], v[114:117]
	v_mfma_f32_16x16x32_bf16 v[114:117], v[146:149], v[212:215], v[114:117]
	s_setprio 0
	s_setprio 1
	v_mfma_f32_16x16x32_bf16 v[62:65], v[150:153], v[86:89], v[62:65]
	v_mfma_f32_16x16x32_bf16 v[62:65], v[154:157], v[182:185], v[62:65]
	v_mfma_f32_16x16x32_bf16 v[54:57], v[150:153], v[192:195], v[54:57]
	v_mfma_f32_16x16x32_bf16 v[54:57], v[154:157], v[196:199], v[54:57]
	v_mfma_f32_16x16x32_bf16 v[46:49], v[150:153], v[200:203], v[46:49]
	v_mfma_f32_16x16x32_bf16 v[46:49], v[154:157], v[204:207], v[46:49]
	v_mfma_f32_16x16x32_bf16 v[38:41], v[150:153], v[208:211], v[38:41]
	v_mfma_f32_16x16x32_bf16 v[38:41], v[154:157], v[212:215], v[38:41]
	v_mfma_f32_16x16x32_bf16 v[58:61], v[158:161], v[86:89], v[58:61]
	v_mfma_f32_16x16x32_bf16 v[58:61], v[178:181], v[182:185], v[58:61]
	v_mfma_f32_16x16x32_bf16 v[50:53], v[158:161], v[192:195], v[50:53]
	v_mfma_f32_16x16x32_bf16 v[50:53], v[178:181], v[196:199], v[50:53]
	v_mfma_f32_16x16x32_bf16 v[42:45], v[158:161], v[200:203], v[42:45]
	v_mfma_f32_16x16x32_bf16 v[42:45], v[178:181], v[204:207], v[42:45]
	v_mfma_f32_16x16x32_bf16 v[34:37], v[158:161], v[208:211], v[34:37]
	v_mfma_f32_16x16x32_bf16 v[34:37], v[178:181], v[212:215], v[34:37]
	s_setprio 0
	s_barrier
; #define PG8_STAGE(bufoff, gbase, voff) do { const char* gb_ = (const char*)(gbase); asm volatile("" : "+s"(gb_)); _Pragma("unroll") for (int _i = 0; _i < 2; ++_i) { unsigned vo_ = (voff)[_i]; asm volatile("" : "+v"(vo_));        \
;         __builtin_amdgcn_global_load_lds((const unsigned*)(gb_ + vo_), (PG8_LAS unsigned*)(lds + (bufoff) + ldsw + _i * 8192), 16, 0, 0); } } while (0)
; #define PG8_LDA(dst, b, h) do { _Pragma("unroll") for (int m = 0; m < 4; ++m) _Pragma("unroll") for (int k = 0; k < 2; ++k) dst[m][k] = *(const PG8_LAS bf16x8*)(lds + PG8_SA(b, h) + aoff + m * 2048 + k * 1024); } while (0)
; #define PG8_MMA(ai, bj, At, Bt) do { __builtin_amdgcn_s_setprio(1); _Pragma("unroll") for (int m = 0; m < 4; ++m) _Pragma("unroll") for (int n = 0; n < 2; ++n) _Pragma("unroll") for (int k = 0; k < 2; ++k) \
;         acc[ai][bj][m][n] = __builtin_amdgcn_mfma_f32_16x16x32_bf16(Bt[n][k], At[m][k], acc[ai][bj][m][n], 0, 0, 0); __builtin_amdgcn_s_setprio(0); } while (0)
; #define PG8_WAIT_V(n) asm volatile("s_waitcnt vmcnt(" #n ")" ::: "memory")
; #define PG8_WAIT_L(n) asm volatile("s_waitcnt lgkmcnt(" #n ")" ::: "memory")
; #define PG8_BAR __builtin_amdgcn_s_barrier()
; #define PG8_SCHED __builtin_amdgcn_sched_barrier(0)
; template <class Epi, class Sched, bool ALIGN_EPI = false, bool SP2 = false>
; __device__ __forceinline__ void gemm_phase(PG8_LAS unsigned char* lds, const Gemm g, const Sched& S, const Epi& E) {
;     ...
;             PG8_LDA(At, 1, 1); PG8_STAGE(PG8_SB(1, 0), b3, voffB); PG8_STAGE(PG8_SB(1, 1), b3 + hstep, voffB); PG8_STAGE(PG8_SA(1, 0), a3, voffA);
;             PG8_WAIT_V(8); PG8_WAIT_L(0); PG8_BAR; PG8_MMA(1, 0, At, B0); PG8_MMA(1, 1, At, B1); PG8_BAR; PG8_SCHED;
;     ...
;         if constexpr (ALIGN_EPI) { if (wr == 0) PG8_BAR; }
	s_add_u32 s0, s8, 0x80
	s_addc_u32 s1, s9, 0
	s_add_i32 s10, s31, s12
	ds_read_b128 v[182:185], v223 offset:49152
	ds_read_b128 v[192:195], v223 offset:50176
	ds_read_b128 v[196:199], v223 offset:51200
	ds_read_b128 v[200:203], v223 offset:52224
	ds_read_b128 v[204:207], v223 offset:53248
	ds_read_b128 v[208:211], v223 offset:54272
	ds_read_b128 v[212:215], v223 offset:55296
	ds_read_b128 v[224:227], v223 offset:56320
	s_mov_b32 m0, s10
	s_nop 0
	global_load_lds_dwordx4 v189, s[0:1] sc0
	s_add_i32 m0, s10, 0x2000
	s_nop 0
	global_load_lds_dwordx4 v219, s[0:1] sc0
	s_add_u32 s0, s8, 0x80080
	s_addc_u32 s1, s9, 0
	s_add_i32 s8, s33, s12
	s_mov_b32 m0, s8
	s_nop 0
	global_load_lds_dwordx4 v189, s[0:1] sc0
	s_add_i32 m0, s8, 0x2000
	s_nop 0
	global_load_lds_dwordx4 v219, s[0:1] sc0
	s_mov_b32 m0, s19
	s_nop 0
	global_load_lds_dwordx4 v1, s[6:7] sc0
	s_mov_b32 m0, s20
	s_nop 0
	global_load_lds_dwordx4 v191, s[6:7] sc0
	s_waitcnt vmcnt(8)
	s_waitcnt lgkmcnt(0)
	s_barrier
	s_setprio 1
	s_waitcnt lgkmcnt(0)
	v_mfma_f32_16x16x32_bf16 v[86:89], v[74:77], v[182:185], v[110:113]
	v_mfma_f32_16x16x32_bf16 v[110:113], v[78:81], v[192:195], v[86:89]
	v_mfma_f32_16x16x32_bf16 v[66:69], v[74:77], v[212:215], v[66:69]
	v_mfma_f32_16x16x32_bf16 v[86:89], v[82:85], v[182:185], v[106:109]
	v_mfma_f32_16x16x32_bf16 v[106:109], v[146:149], v[192:195], v[86:89]
	v_mfma_f32_16x16x32_bf16 v[86:89], v[74:77], v[196:199], v[102:105]
	v_mfma_f32_16x16x32_bf16 v[102:105], v[78:81], v[200:203], v[86:89]
	v_mfma_f32_16x16x32_bf16 v[86:89], v[82:85], v[196:199], v[98:101]
	v_mfma_f32_16x16x32_bf16 v[98:101], v[146:149], v[200:203], v[86:89]
	v_mfma_f32_16x16x32_bf16 v[86:89], v[74:77], v[204:207], v[94:97]
	v_mfma_f32_16x16x32_bf16 v[94:97], v[78:81], v[208:211], v[86:89]
	v_mfma_f32_16x16x32_bf16 v[86:89], v[82:85], v[204:207], v[90:93]
	v_mfma_f32_16x16x32_bf16 v[90:93], v[146:149], v[208:211], v[86:89]
	v_mfma_f32_16x16x32_bf16 v[86:89], v[78:81], v[224:227], v[66:69]
	v_mfma_f32_16x16x32_bf16 v[66:69], v[82:85], v[212:215], v[70:73]
	v_mfma_f32_16x16x32_bf16 v[82:85], v[146:149], v[224:227], v[66:69]
	s_setprio 0
	s_setprio 1
	v_mfma_f32_16x16x32_bf16 v[30:33], v[150:153], v[182:185], v[30:33]
	v_mfma_f32_16x16x32_bf16 v[30:33], v[154:157], v[192:195], v[30:33]
	v_mfma_f32_16x16x32_bf16 v[22:25], v[150:153], v[196:199], v[22:25]
	v_mfma_f32_16x16x32_bf16 v[22:25], v[154:157], v[200:203], v[22:25]
	v_mfma_f32_16x16x32_bf16 v[14:17], v[150:153], v[204:207], v[14:17]
	v_mfma_f32_16x16x32_bf16 v[14:17], v[154:157], v[208:211], v[14:17]
	v_mfma_f32_16x16x32_bf16 v[6:9], v[150:153], v[212:215], v[6:9]
	v_mfma_f32_16x16x32_bf16 v[6:9], v[154:157], v[224:227], v[6:9]
	v_mfma_f32_16x16x32_bf16 v[26:29], v[158:161], v[182:185], v[26:29]
	v_mfma_f32_16x16x32_bf16 v[26:29], v[178:181], v[192:195], v[26:29]
	v_mfma_f32_16x16x32_bf16 v[18:21], v[158:161], v[196:199], v[18:21]
	v_mfma_f32_16x16x32_bf16 v[18:21], v[178:181], v[200:203], v[18:21]
	v_mfma_f32_16x16x32_bf16 v[10:13], v[158:161], v[204:207], v[10:13]
	v_mfma_f32_16x16x32_bf16 v[10:13], v[178:181], v[208:211], v[10:13]
	v_mfma_f32_16x16x32_bf16 v[2:5], v[158:161], v[212:215], v[2:5]
	v_mfma_f32_16x16x32_bf16 v[2:5], v[178:181], v[224:227], v[2:5]
	s_setprio 0
	s_barrier
	s_add_i32 s30, s30, 2
	s_add_u32 s28, s28, 0x100
	s_addc_u32 s29, s29, 0
	s_cmp_gt_u32 s30, 29
	s_mov_b64 s[0:1], s[2:3]
	s_cbranch_scc0 .LBB0_232
	s_and_b64 vcc, exec, s[44:45]
	s_cbranch_vccz .LBB0_235
	s_barrier

; #define PG8_STAGE(bufoff, gbase, voff) do { const char* gb_ = (const char*)(gbase); asm volatile("" : "+s"(gb_)); _Pragma("unroll") for (int _i = 0; _i < 2; ++_i) { unsigned vo_ = (voff)[_i]; asm volatile("" : "+v"(vo_));        \
;         __builtin_amdgcn_global_load_lds((const unsigned*)(gb_ + vo_), (PG8_LAS unsigned*)(lds + (bufoff) + ldsw + _i * 8192), 16, 0, 0); } } while (0)
; #define PG8_LDA(dst, b, h) do { _Pragma("unroll") for (int m = 0; m < 4; ++m) _Pragma("unroll") for (int k = 0; k < 2; ++k) dst[m][k] = *(const PG8_LAS bf16x8*)(lds + PG8_SA(b, h) + aoff + m * 2048 + k * 1024); } while (0)
; #define PG8_LDB(dst, b, h) do { _Pragma("unroll") for (int n = 0; n < 2; ++n) _Pragma("unroll") for (int k = 0; k < 2; ++k) dst[n][k] = *(const PG8_LAS bf16x8*)(lds + PG8_SB(b, h) + boff + n * 2048 + k * 1024); } while (0)
; #define PG8_MMA(ai, bj, At, Bt) do { __builtin_amdgcn_s_setprio(1); _Pragma("unroll") for (int m = 0; m < 4; ++m) _Pragma("unroll") for (int n = 0; n < 2; ++n) _Pragma("unroll") for (int k = 0; k < 2; ++k) \
;         acc[ai][bj][m][n] = __builtin_amdgcn_mfma_f32_16x16x32_bf16(Bt[n][k], At[m][k], acc[ai][bj][m][n], 0, 0, 0); __builtin_amdgcn_s_setprio(0); } while (0)
; #define PG8_WAIT_V(n) asm volatile("s_waitcnt vmcnt(" #n ")" ::: "memory")
; template <class Epi, class Sched, bool ALIGN_EPI = false, bool SP2 = false>
; __device__ __forceinline__ void gemm_phase(PG8_LAS unsigned char* lds, const Gemm g, const Sched& S, const Epi& E) {
;     ...
;             const bool last = (t == nt - 2);
;             const char* a1 = cA + (size_t)(t + 1) * kstep;
;             const char* a2 = last ? nA : cA + (size_t)(t + 2) * kstep; const char* b2 = last ? nB : cB + (size_t)(t + 2) * kstep;
;             const char* a3 = a2 + kstep; const char* b3 = b2 + kstep;
;             if (last && has_next) S.a_ready(nxt);
;             if constexpr (SP2) {
;             PG8_LDB(B0, 0, 0); PG8_LDB(B1, 0, 1); PG8_SCHED; PG8_LDA(At, 0, 0); PG8_STAGE(PG8_SA(1, 1), a1 + hstep, voffA);
;             PG8_WAIT_V(8); PG8_WAIT_L(0); PG8_BAR; PG8_MMA(0, 0, At, B0); PG8_MMA(0, 1, At, B1); PG8_BAR; PG8_SCHED;
;             PG8_LDA(At, 0, 1); PG8_STAGE(PG8_SB(0, 0), b2, voffB); PG8_STAGE(PG8_SB(0, 1), b2 + hstep, voffB); PG8_STAGE(PG8_SA(0, 0), a2, voffA);
;             PG8_WAIT_V(8); PG8_WAIT_L(0); PG8_BAR; PG8_MMA(1, 0, At, B0); PG8_MMA(1, 1, At, B1); PG8_BAR; PG8_SCHED;
.LBB0_555:
	s_add_u32 s6, s4, 0x100
	s_addc_u32 s7, s5, 0
	s_cmp_eq_u32 s51, 28
	s_cselect_b32 s12, s35, s6
	s_cselect_b32 s13, s34, s7
	s_cselect_b32 s10, s39, s40
	s_cselect_b32 s11, s38, s49
	s_add_u32 s8, s12, 0x80
	s_addc_u32 s9, s13, 0
	s_add_i32 s56, 0, 0x10000
	s_add_i32 s57, 0, 0x14000
	ds_read_b128 v[26:29], v244
	ds_read_b128 v[30:33], v244 offset:1024
	ds_read_b128 v[98:101], v244 offset:2048
	ds_read_b128 v[102:105], v244 offset:3072
	ds_read_b128 v[146:149], v244 offset:16384
	ds_read_b128 v[150:153], v244 offset:17408
	ds_read_b128 v[154:157], v244 offset:18432
	ds_read_b128 v[158:161], v244 offset:19456
	s_add_u32 s4, s4, 0x80080
	s_addc_u32 s5, s5, 0
	ds_read_b128 v[178:181], v210
	ds_read_b128 v[182:185], v210 offset:1024
	ds_read_b128 v[186:189], v210 offset:2048
	ds_read_b128 v[190:193], v210 offset:3072
	ds_read_b128 v[194:197], v210 offset:4096
	ds_read_b128 v[198:201], v210 offset:5120
	ds_read_b128 v[202:205], v210 offset:6144
	ds_read_b128 v[212:215], v210 offset:7168
	s_add_i32 m0, s18, 0xc000
	s_nop 0
	global_load_lds_dwordx4 v1, s[4:5] sc0
	s_add_i32 m0, s18, 0xe000
	s_nop 0
	global_load_lds_dwordx4 v164, s[4:5] sc0
	s_waitcnt vmcnt(8)
	s_waitcnt lgkmcnt(0)
	s_barrier
	s_setprio 1
	s_waitcnt lgkmcnt(0)
	v_mfma_f32_16x16x32_bf16 v[142:145], v[26:29], v[178:181], v[142:145]
	v_mfma_f32_16x16x32_bf16 v[142:145], v[30:33], v[182:185], v[142:145]
	v_mfma_f32_16x16x32_bf16 v[134:137], v[26:29], v[186:189], v[134:137]
	v_mfma_f32_16x16x32_bf16 v[134:137], v[30:33], v[190:193], v[134:137]
	v_mfma_f32_16x16x32_bf16 v[126:129], v[26:29], v[194:197], v[126:129]
	v_mfma_f32_16x16x32_bf16 v[126:129], v[30:33], v[198:201], v[126:129]
	v_mfma_f32_16x16x32_bf16 v[118:121], v[26:29], v[202:205], v[118:121]
	v_mfma_f32_16x16x32_bf16 v[118:121], v[30:33], v[212:215], v[118:121]
	v_mfma_f32_16x16x32_bf16 v[138:141], v[98:101], v[178:181], v[138:141]
	v_mfma_f32_16x16x32_bf16 v[138:141], v[102:105], v[182:185], v[138:141]
	v_mfma_f32_16x16x32_bf16 v[130:133], v[98:101], v[186:189], v[130:133]
	v_mfma_f32_16x16x32_bf16 v[130:133], v[102:105], v[190:193], v[130:133]
	v_mfma_f32_16x16x32_bf16 v[122:125], v[98:101], v[194:197], v[122:125]
	v_mfma_f32_16x16x32_bf16 v[122:125], v[102:105], v[198:201], v[122:125]
	v_mfma_f32_16x16x32_bf16 v[114:117], v[98:101], v[202:205], v[114:117]
	v_mfma_f32_16x16x32_bf16 v[114:117], v[102:105], v[212:215], v[114:117]
	s_setprio 0
	s_setprio 1
	v_mfma_f32_16x16x32_bf16 v[70:73], v[146:149], v[178:181], v[70:73]
	v_mfma_f32_16x16x32_bf16 v[70:73], v[150:153], v[182:185], v[70:73]
	v_mfma_f32_16x16x32_bf16 v[62:65], v[146:149], v[186:189], v[62:65]
	v_mfma_f32_16x16x32_bf16 v[62:65], v[150:153], v[190:193], v[62:65]
	v_mfma_f32_16x16x32_bf16 v[54:57], v[146:149], v[194:197], v[54:57]
	v_mfma_f32_16x16x32_bf16 v[54:57], v[150:153], v[198:201], v[54:57]
	v_mfma_f32_16x16x32_bf16 v[46:49], v[146:149], v[202:205], v[46:49]
	v_mfma_f32_16x16x32_bf16 v[46:49], v[150:153], v[212:215], v[46:49]
	v_mfma_f32_16x16x32_bf16 v[66:69], v[154:157], v[178:181], v[66:69]
	v_mfma_f32_16x16x32_bf16 v[66:69], v[158:161], v[182:185], v[66:69]
	v_mfma_f32_16x16x32_bf16 v[58:61], v[154:157], v[186:189], v[58:61]
	v_mfma_f32_16x16x32_bf16 v[58:61], v[158:161], v[190:193], v[58:61]
	v_mfma_f32_16x16x32_bf16 v[50:53], v[154:157], v[194:197], v[50:53]
	v_mfma_f32_16x16x32_bf16 v[50:53], v[158:161], v[198:201], v[50:53]
	v_mfma_f32_16x16x32_bf16 v[42:45], v[154:157], v[202:205], v[42:45]
	v_mfma_f32_16x16x32_bf16 v[42:45], v[158:161], v[212:215], v[42:45]
	s_setprio 0
	s_barrier
	s_mov_b64 s[4:5], s[10:11]
	s_add_i32 s56, s56, s17
	ds_read_b128 v[178:181], v210 offset:16384
	ds_read_b128 v[182:185], v210 offset:17408
	ds_read_b128 v[186:189], v210 offset:18432
	ds_read_b128 v[190:193], v210 offset:19456
	ds_read_b128 v[194:197], v210 offset:20480
	ds_read_b128 v[198:201], v210 offset:21504
	ds_read_b128 v[202:205], v210 offset:22528
	ds_read_b128 v[212:215], v210 offset:23552
	s_mov_b32 m0, s56
	s_nop 0
	global_load_lds_dwordx4 v162, s[4:5] sc0
	s_add_i32 m0, s56, 0x2000
	s_nop 0
	global_load_lds_dwordx4 v206, s[4:5] sc0
	s_add_u32 s4, s10, 0x80000
	s_addc_u32 s5, s11, 0
	s_add_i32 s56, s57, s17
	s_mov_b32 m0, s56
	s_nop 0
	global_load_lds_dwordx4 v162, s[4:5] sc0
	s_add_i32 m0, s56, 0x2000
	s_nop 0
	global_load_lds_dwordx4 v206, s[4:5] sc0
	s_mov_b64 s[4:5], s[12:13]
	s_mov_b32 m0, s18
	s_nop 0
	global_load_lds_dwordx4 v1, s[4:5] sc0
	s_mov_b32 m0, s19
	s_nop 0
	global_load_lds_dwordx4 v164, s[4:5] sc0
	s_waitcnt vmcnt(8)
	s_waitcnt lgkmcnt(0)
	s_barrier
; #define PG8_STAGE(bufoff, gbase, voff) do { const char* gb_ = (const char*)(gbase); asm volatile("" : "+s"(gb_)); _Pragma("unroll") for (int _i = 0; _i < 2; ++_i) { unsigned vo_ = (voff)[_i]; asm volatile("" : "+v"(vo_));        \
;         __builtin_amdgcn_global_load_lds((const unsigned*)(gb_ + vo_), (PG8_LAS unsigned*)(lds + (bufoff) + ldsw + _i * 8192), 16, 0, 0); } } while (0)
; #define PG8_LDA(dst, b, h) do { _Pragma("unroll") for (int m = 0; m < 4; ++m) _Pragma("unroll") for (int k = 0; k < 2; ++k) dst[m][k] = *(const PG8_LAS bf16x8*)(lds + PG8_SA(b, h) + aoff + m * 2048 + k * 1024); } while (0)
; #define PG8_LDB(dst, b, h) do { _Pragma("unroll") for (int n = 0; n < 2; ++n) _Pragma("unroll") for (int k = 0; k < 2; ++k) dst[n][k] = *(const PG8_LAS bf16x8*)(lds + PG8_SB(b, h) + boff + n * 2048 + k * 1024); } while (0)
; #define PG8_MMA(ai, bj, At, Bt) do { __builtin_amdgcn_s_setprio(1); _Pragma("unroll") for (int m = 0; m < 4; ++m) _Pragma("unroll") for (int n = 0; n < 2; ++n) _Pragma("unroll") for (int k = 0; k < 2; ++k) \
;         acc[ai][bj][m][n] = __builtin_amdgcn_mfma_f32_16x16x32_bf16(Bt[n][k], At[m][k], acc[ai][bj][m][n], 0, 0, 0); __builtin_amdgcn_s_setprio(0); } while (0)
; #define PG8_WAIT_V(n) asm volatile("s_waitcnt vmcnt(" #n ")" ::: "memory")
; #define PG8_WAIT_L(n) asm volatile("s_waitcnt lgkmcnt(" #n ")" ::: "memory")
; #define PG8_BAR __builtin_amdgcn_s_barrier()
; #define PG8_SCHED __builtin_amdgcn_sched_barrier(0)
; template <class Epi, class Sched, bool ALIGN_EPI = false, bool SP2 = false>
; __device__ __forceinline__ void gemm_phase(PG8_LAS unsigned char* lds, const Gemm g, const Sched& S, const Epi& E) {
;     ...
;             PG8_WAIT_V(8); PG8_WAIT_L(0); PG8_BAR; PG8_MMA(1, 0, At, B0); PG8_MMA(1, 1, At, B1); PG8_BAR; PG8_SCHED;
;             PG8_LDB(B0, 1, 0); PG8_LDB(B1, 1, 1); PG8_SCHED; PG8_LDA(At, 1, 0); PG8_STAGE(PG8_SA(0, 1), a2 + hstep, voffA);
;             PG8_WAIT_V(8); PG8_WAIT_L(0); PG8_BAR; PG8_MMA(0, 0, At, B0); PG8_MMA(0, 1, At, B1); PG8_BAR; PG8_SCHED;
	s_setprio 1
	s_waitcnt lgkmcnt(0)
	v_mfma_f32_16x16x32_bf16 v[110:113], v[26:29], v[178:181], v[110:113]
	v_mfma_f32_16x16x32_bf16 v[110:113], v[30:33], v[182:185], v[110:113]
	v_mfma_f32_16x16x32_bf16 v[94:97], v[26:29], v[186:189], v[94:97]
	v_mfma_f32_16x16x32_bf16 v[94:97], v[30:33], v[190:193], v[94:97]
	v_mfma_f32_16x16x32_bf16 v[86:89], v[26:29], v[194:197], v[86:89]
	v_mfma_f32_16x16x32_bf16 v[86:89], v[30:33], v[198:201], v[86:89]
	v_mfma_f32_16x16x32_bf16 v[26:29], v[26:29], v[202:205], v[78:81]
	v_mfma_f32_16x16x32_bf16 v[26:29], v[30:33], v[212:215], v[26:29]
	v_mfma_f32_16x16x32_bf16 v[106:109], v[98:101], v[178:181], v[106:109]
	v_mfma_f32_16x16x32_bf16 v[106:109], v[102:105], v[182:185], v[106:109]
	v_mfma_f32_16x16x32_bf16 v[90:93], v[98:101], v[186:189], v[90:93]
	v_mfma_f32_16x16x32_bf16 v[90:93], v[102:105], v[190:193], v[90:93]
	v_mfma_f32_16x16x32_bf16 v[82:85], v[98:101], v[194:197], v[82:85]
	v_mfma_f32_16x16x32_bf16 v[82:85], v[102:105], v[198:201], v[82:85]
	v_mfma_f32_16x16x32_bf16 v[30:33], v[98:101], v[202:205], v[74:77]
	v_mfma_f32_16x16x32_bf16 v[30:33], v[102:105], v[212:215], v[30:33]
	s_setprio 0
	s_setprio 1
	v_mfma_f32_16x16x32_bf16 v[38:41], v[146:149], v[178:181], v[38:41]
	v_mfma_f32_16x16x32_bf16 v[38:41], v[150:153], v[182:185], v[38:41]
	v_mfma_f32_16x16x32_bf16 v[22:25], v[146:149], v[186:189], v[22:25]
	v_mfma_f32_16x16x32_bf16 v[22:25], v[150:153], v[190:193], v[22:25]
	v_mfma_f32_16x16x32_bf16 v[14:17], v[146:149], v[194:197], v[14:17]
	v_mfma_f32_16x16x32_bf16 v[14:17], v[150:153], v[198:201], v[14:17]
	v_mfma_f32_16x16x32_bf16 v[6:9], v[146:149], v[202:205], v[6:9]
	v_mfma_f32_16x16x32_bf16 v[6:9], v[150:153], v[212:215], v[6:9]
	v_mfma_f32_16x16x32_bf16 v[34:37], v[154:157], v[178:181], v[34:37]
	v_mfma_f32_16x16x32_bf16 v[34:37], v[158:161], v[182:185], v[34:37]
	v_mfma_f32_16x16x32_bf16 v[18:21], v[154:157], v[186:189], v[18:21]
	v_mfma_f32_16x16x32_bf16 v[18:21], v[158:161], v[190:193], v[18:21]
	v_mfma_f32_16x16x32_bf16 v[10:13], v[154:157], v[194:197], v[10:13]
	v_mfma_f32_16x16x32_bf16 v[10:13], v[158:161], v[198:201], v[10:13]
	v_mfma_f32_16x16x32_bf16 v[2:5], v[154:157], v[202:205], v[2:5]
	v_mfma_f32_16x16x32_bf16 v[2:5], v[158:161], v[212:215], v[2:5]
	s_setprio 0
	s_barrier
	s_add_i32 s56, 0, 0x18000
	s_add_i32 s57, 0, 0x1c000
	ds_read_b128 v[74:77], v244 offset:32768
	ds_read_b128 v[78:81], v244 offset:33792
	ds_read_b128 v[98:101], v244 offset:34816
	ds_read_b128 v[102:105], v244 offset:35840
	ds_read_b128 v[146:149], v244 offset:49152
	ds_read_b128 v[150:153], v244 offset:50176
	ds_read_b128 v[154:157], v244 offset:51200
	ds_read_b128 v[158:161], v244 offset:52224
	s_add_u32 s4, s12, 0x80000
	s_addc_u32 s5, s13, 0
	s_mov_b32 m0, s20
	ds_read_b128 v[178:181], v210 offset:32768
	ds_read_b128 v[182:185], v210 offset:33792
	ds_read_b128 v[186:189], v210 offset:34816
	ds_read_b128 v[190:193], v210 offset:35840
	ds_read_b128 v[194:197], v210 offset:36864
	ds_read_b128 v[198:201], v210 offset:37888
	ds_read_b128 v[202:205], v210 offset:38912
	ds_read_b128 v[212:215], v210 offset:39936
	s_nop 0
	global_load_lds_dwordx4 v1, s[4:5] sc0
	s_mov_b32 m0, s21
	s_nop 0
	global_load_lds_dwordx4 v164, s[4:5] sc0
	s_waitcnt vmcnt(8)
	s_waitcnt lgkmcnt(0)
	s_barrier
	s_setprio 1
	s_waitcnt lgkmcnt(0)
	v_mfma_f32_16x16x32_bf16 v[142:145], v[74:77], v[178:181], v[142:145]
	v_mfma_f32_16x16x32_bf16 v[142:145], v[78:81], v[182:185], v[142:145]
	v_mfma_f32_16x16x32_bf16 v[134:137], v[74:77], v[186:189], v[134:137]
	v_mfma_f32_16x16x32_bf16 v[134:137], v[78:81], v[190:193], v[134:137]
	v_mfma_f32_16x16x32_bf16 v[126:129], v[74:77], v[194:197], v[126:129]
	v_mfma_f32_16x16x32_bf16 v[126:129], v[78:81], v[198:201], v[126:129]
	v_mfma_f32_16x16x32_bf16 v[118:121], v[74:77], v[202:205], v[118:121]
	v_mfma_f32_16x16x32_bf16 v[118:121], v[78:81], v[212:215], v[118:121]
	v_mfma_f32_16x16x32_bf16 v[138:141], v[98:101], v[178:181], v[138:141]
	v_mfma_f32_16x16x32_bf16 v[138:141], v[102:105], v[182:185], v[138:141]
	v_mfma_f32_16x16x32_bf16 v[130:133], v[98:101], v[186:189], v[130:133]
	v_mfma_f32_16x16x32_bf16 v[130:133], v[102:105], v[190:193], v[130:133]
	v_mfma_f32_16x16x32_bf16 v[122:125], v[98:101], v[194:197], v[122:125]
	v_mfma_f32_16x16x32_bf16 v[122:125], v[102:105], v[198:201], v[122:125]
	v_mfma_f32_16x16x32_bf16 v[114:117], v[98:101], v[202:205], v[114:117]
	v_mfma_f32_16x16x32_bf16 v[114:117], v[102:105], v[212:215], v[114:117]
	s_setprio 0
	s_setprio 1
	v_mfma_f32_16x16x32_bf16 v[70:73], v[146:149], v[178:181], v[70:73]
	v_mfma_f32_16x16x32_bf16 v[70:73], v[150:153], v[182:185], v[70:73]
	v_mfma_f32_16x16x32_bf16 v[62:65], v[146:149], v[186:189], v[62:65]
	v_mfma_f32_16x16x32_bf16 v[62:65], v[150:153], v[190:193], v[62:65]
	v_mfma_f32_16x16x32_bf16 v[54:57], v[146:149], v[194:197], v[54:57]
	v_mfma_f32_16x16x32_bf16 v[54:57], v[150:153], v[198:201], v[54:57]
	v_mfma_f32_16x16x32_bf16 v[46:49], v[146:149], v[202:205], v[46:49]
	v_mfma_f32_16x16x32_bf16 v[46:49], v[150:153], v[212:215], v[46:49]
	v_mfma_f32_16x16x32_bf16 v[66:69], v[154:157], v[178:181], v[66:69]
	v_mfma_f32_16x16x32_bf16 v[66:69], v[158:161], v[182:185], v[66:69]
	v_mfma_f32_16x16x32_bf16 v[58:61], v[154:157], v[186:189], v[58:61]
	v_mfma_f32_16x16x32_bf16 v[58:61], v[158:161], v[190:193], v[58:61]
	v_mfma_f32_16x16x32_bf16 v[50:53], v[154:157], v[194:197], v[50:53]
	v_mfma_f32_16x16x32_bf16 v[50:53], v[158:161], v[198:201], v[50:53]
	v_mfma_f32_16x16x32_bf16 v[42:45], v[154:157], v[202:205], v[42:45]
	v_mfma_f32_16x16x32_bf16 v[42:45], v[158:161], v[212:215], v[42:45]
	s_setprio 0
	s_barrier
;     __device__ __forceinline__ void operator()(const f32x4 (&acc)[2][2][4][2], const Unit& u, int wr, int wc, int fr, int fq) const {
;         const int row0 = u.pm * BM + wr * 64 + fr, col0 = u.pn * BM + wc * 32 + 8 * fq, b = (u.pm * BM) / rows_per_batch;
;         const float* g = gate + (size_t)b * gate_bstride + col0;
;         float ssq[2][4];
; #pragma unroll
;         for (int ai = 0; ai < 2; ++ai)
; #pragma unroll
;             for (int m = 0; m < 4; ++m) ssq[ai][m] = 0.f;
;         f32x4 gv[2][2], Gv[2][2];
; #pragma unroll
;         for (int bj = 0; bj < 2; ++bj) { gv[bj][0] = *(const f32x4*)(g + bj * HALF); gv[bj][1] = *(const f32x4*)(g + bj * HALF + 4); Gv[bj][0] = (f32x4){0.f, 0.f, 0.f, 0.f}; Gv[bj][1] = (f32x4){0.f, 0.f, 0.f, 0.f};
;             if (Hn) { const float* sc = scnext + (size_t)b * gate_bstride + col0 + bj * HALF;
;                 Gv[bj][0] = *(const f32x4*)(gnext + col0 + bj * HALF) * (1.0f + *(const f32x4*)(sc)); Gv[bj][1] = *(const f32x4*)(gnext + col0 + bj * HALF + 4) * (1.0f + *(const f32x4*)(sc + 4)); } }
; #pragma unroll
;         for (int bj = 0; bj < 2; ++bj) {
;             const f32x4 g0 = gv[bj][0], g1 = gv[bj][1], G0 = Gv[bj][0], G1 = Gv[bj][1];
; #pragma unroll
;             for (int ai = 0; ai < 2; ++ai)
; #pragma unroll
;                 for (int m = 0; m < 4; ++m) { const size_t off = (size_t)(row0 + ai * HALF + m * 16) * 2048 + col0 + bj * HALF;
;                     f32x4 x0 = __builtin_nontemporal_load((const f32x4*)(base + off)), x1 = __builtin_nontemporal_load((const f32x4*)(base + off + 4));
;                     if constexpr (HAS_DIN) { const u32x4 dw = __builtin_nontemporal_load((const u32x4*)(dbuf + off));
;                         x0 += (f32x4){__builtin_bit_cast(float, dw.x << 16), __builtin_bit_cast(float, dw.x & 0xffff0000u), __builtin_bit_cast(float, dw.y << 16), __builtin_bit_cast(float, dw.y & 0xffff0000u)};
; template <class Epi, class Sched, bool ALIGN_EPI = false, bool SP2 = false>
; __device__ __forceinline__ void gemm_phase(PG8_LAS unsigned char* lds, const Gemm g, const Sched& S, const Epi& E) {
;     ...
;             PG8_LDA(At, 1, 1); PG8_STAGE(PG8_SB(1, 0), b3, voffB); PG8_STAGE(PG8_SB(1, 1), b3 + hstep, voffB); PG8_STAGE(PG8_SA(1, 0), a3, voffA);
;             PG8_WAIT_V(8); PG8_WAIT_L(0); PG8_BAR; PG8_MMA(1, 0, At, B0); PG8_MMA(1, 1, At, B1); PG8_BAR; PG8_SCHED;
	s_add_u32 s4, s10, 0x80
	s_addc_u32 s5, s11, 0
	s_add_i32 s12, s56, s17
	ds_read_b128 v[178:181], v210 offset:49152
	ds_read_b128 v[182:185], v210 offset:50176
	ds_read_b128 v[186:189], v210 offset:51200
	ds_read_b128 v[190:193], v210 offset:52224
	ds_read_b128 v[194:197], v210 offset:53248
	ds_read_b128 v[198:201], v210 offset:54272
	ds_read_b128 v[202:205], v210 offset:55296
	ds_read_b128 v[212:215], v210 offset:56320
	s_mov_b32 m0, s12
	s_nop 0
	global_load_lds_dwordx4 v162, s[4:5] sc0
	s_add_i32 m0, s12, 0x2000
	s_nop 0
	global_load_lds_dwordx4 v206, s[4:5] sc0
	s_add_u32 s4, s10, 0x80080
	s_addc_u32 s5, s11, 0
	s_add_i32 s10, s57, s17
	s_mov_b32 m0, s10
	s_nop 0
	global_load_lds_dwordx4 v162, s[4:5] sc0
	s_add_i32 m0, s10, 0x2000
	s_nop 0
	global_load_lds_dwordx4 v206, s[4:5] sc0
	s_mov_b32 m0, s26
	s_nop 0
	global_load_lds_dwordx4 v1, s[8:9] sc0
	s_mov_b32 m0, s27
	s_nop 0
	global_load_lds_dwordx4 v164, s[8:9] sc0
	s_waitcnt vmcnt(8)
	s_waitcnt lgkmcnt(0)
	s_barrier
	s_setprio 1
	s_waitcnt lgkmcnt(0)
	v_mfma_f32_16x16x32_bf16 v[110:113], v[74:77], v[178:181], v[110:113]
	v_mfma_f32_16x16x32_bf16 v[110:113], v[78:81], v[182:185], v[110:113]
	v_mfma_f32_16x16x32_bf16 v[94:97], v[74:77], v[186:189], v[94:97]
	v_mfma_f32_16x16x32_bf16 v[94:97], v[78:81], v[190:193], v[94:97]
	v_mfma_f32_16x16x32_bf16 v[86:89], v[74:77], v[194:197], v[86:89]
	v_mfma_f32_16x16x32_bf16 v[86:89], v[78:81], v[198:201], v[86:89]
	v_mfma_f32_16x16x32_bf16 v[26:29], v[74:77], v[202:205], v[26:29]
	v_mfma_f32_16x16x32_bf16 v[78:81], v[78:81], v[212:215], v[26:29]
	v_mfma_f32_16x16x32_bf16 v[106:109], v[98:101], v[178:181], v[106:109]
	v_mfma_f32_16x16x32_bf16 v[106:109], v[102:105], v[182:185], v[106:109]
	v_mfma_f32_16x16x32_bf16 v[90:93], v[98:101], v[186:189], v[90:93]
	v_mfma_f32_16x16x32_bf16 v[90:93], v[102:105], v[190:193], v[90:93]
	v_mfma_f32_16x16x32_bf16 v[82:85], v[98:101], v[194:197], v[82:85]
	v_mfma_f32_16x16x32_bf16 v[82:85], v[102:105], v[198:201], v[82:85]
	v_mfma_f32_16x16x32_bf16 v[26:29], v[98:101], v[202:205], v[30:33]
	v_mfma_f32_16x16x32_bf16 v[74:77], v[102:105], v[212:215], v[26:29]
	s_setprio 0
	s_setprio 1
	v_mfma_f32_16x16x32_bf16 v[26:29], v[146:149], v[178:181], v[38:41]
	v_mfma_f32_16x16x32_bf16 v[38:41], v[150:153], v[182:185], v[26:29]
	v_mfma_f32_16x16x32_bf16 v[22:25], v[146:149], v[186:189], v[22:25]
	v_mfma_f32_16x16x32_bf16 v[22:25], v[150:153], v[190:193], v[22:25]
	v_mfma_f32_16x16x32_bf16 v[14:17], v[146:149], v[194:197], v[14:17]
	v_mfma_f32_16x16x32_bf16 v[14:17], v[150:153], v[198:201], v[14:17]
	v_mfma_f32_16x16x32_bf16 v[6:9], v[146:149], v[202:205], v[6:9]
	v_mfma_f32_16x16x32_bf16 v[6:9], v[150:153], v[212:215], v[6:9]
	v_mfma_f32_16x16x32_bf16 v[26:29], v[154:157], v[178:181], v[34:37]
	v_mfma_f32_16x16x32_bf16 v[34:37], v[158:161], v[182:185], v[26:29]
	v_mfma_f32_16x16x32_bf16 v[18:21], v[154:157], v[186:189], v[18:21]
	v_mfma_f32_16x16x32_bf16 v[18:21], v[158:161], v[190:193], v[18:21]
	v_mfma_f32_16x16x32_bf16 v[10:13], v[154:157], v[194:197], v[10:13]
	v_mfma_f32_16x16x32_bf16 v[10:13], v[158:161], v[198:201], v[10:13]
	v_mfma_f32_16x16x32_bf16 v[2:5], v[154:157], v[202:205], v[2:5]
	v_mfma_f32_16x16x32_bf16 v[2:5], v[158:161], v[212:215], v[2:5]
	s_setprio 0
	s_barrier
	s_add_i32 s51, s51, 2
	s_add_u32 s40, s40, 0x100
	s_addc_u32 s49, s49, 0
	s_cmp_gt_u32 s51, 29
	s_mov_b64 s[4:5], s[6:7]
	s_cbranch_scc0 .LBB0_555
	s_ashr_i32 s4, s29, 31
	s_lshr_b32 s4, s4, 27
	s_add_i32 s4, s29, s4
	s_ashr_i32 s4, s4, 5
	v_lshl_or_b32 v148, s33, 8, v209
	s_mul_i32 s7, s4, 0xc000
	v_ashrrev_i32_e32 v149, 31, v148
	s_mul_hi_i32 s6, s4, 0xc000
	s_add_u32 s4, s22, s7
	s_addc_u32 s5, s23, s6
	v_lshlrev_b64 v[26:27], 2, v[148:149]
	v_lshl_add_u64 v[146:147], s[4:5], 0, v[26:27]
	s_add_u32 s4, s24, s7
	s_addc_u32 s5, s25, s6
	v_lshl_add_u64 v[160:161], s[4:5], 0, v[26:27]
	v_lshl_add_u64 v[178:179], s[46:47], 0, v[26:27]
	global_load_dwordx4 v[98:101], v[146:147], off offset:16
	global_load_dwordx4 v[102:105], v[146:147], off
	global_load_dwordx4 v[26:29], v[178:179], off offset:16
	global_load_dwordx4 v[30:33], v[178:179], off
	global_load_dwordx4 v[150:153], v[160:161], off offset:16
	global_load_dwordx4 v[154:157], v[160:161], off
	s_mov_b64 s[4:5], 0x40000
	s_waitcnt vmcnt(0)
	v_pk_mul_f32 v[188:189], v[140:141], v[100:101]
	v_pk_mul_f32 v[142:143], v[142:143], v[102:103]
	v_pk_mul_f32 v[144:145], v[144:145], v[104:105]
	v_pk_mul_f32 v[140:141], v[138:139], v[98:99]
	v_pk_mul_f32 v[136:137], v[136:137], v[104:105]
	v_pk_add_f32 v[156:157], v[156:157], 1.0 op_sel_hi:[1,0]
	v_pk_add_f32 v[154:155], v[154:155], 1.0 op_sel_hi:[1,0]
	v_pk_mul_f32 v[198:199], v[32:33], v[156:157]
	v_pk_mul_f32 v[200:201], v[30:31], v[154:155]
	v_pk_add_f32 v[30:31], v[152:153], 1.0 op_sel_hi:[1,0]
	v_pk_add_f32 v[32:33], v[150:151], 1.0 op_sel_hi:[1,0]
	v_pk_mul_f32 v[202:203], v[28:29], v[30:31]
	v_pk_mul_f32 v[204:205], v[26:27], v[32:33]
	global_load_dwordx4 v[26:29], v[146:147], off offset:528
	global_load_dwordx4 v[30:33], v[146:147], off offset:512
	global_load_dwordx4 v[156:159], v[178:179], off offset:528
	global_load_dwordx4 v[152:155], v[178:179], off offset:512
	s_nop 0
	global_load_dwordx4 v[178:181], v[160:161], off offset:528
	global_load_dwordx4 v[182:185], v[160:161], off offset:512
	v_pk_mul_f32 v[134:135], v[134:135], v[102:103]
	v_pk_mul_f32 v[130:131], v[130:131], v[98:99]
	v_pk_mul_f32 v[132:133], v[132:133], v[100:101]
	v_pk_mul_f32 v[128:129], v[128:129], v[104:105]
	v_pk_mul_f32 v[126:127], v[126:127], v[102:103]
	v_pk_mul_f32 v[122:123], v[122:123], v[98:99]
	v_pk_mul_f32 v[124:125], v[124:125], v[100:101]
	v_pk_mul_f32 v[120:121], v[120:121], v[104:105]
	v_pk_mul_f32 v[118:119], v[118:119], v[102:103]
	v_pk_mul_f32 v[114:115], v[114:115], v[98:99]
	v_pk_mul_f32 v[116:117], v[116:117], v[100:101]
	v_pk_mul_f32 v[112:113], v[112:113], v[104:105]
	v_pk_mul_f32 v[110:111], v[110:111], v[102:103]
	v_pk_mul_f32 v[106:107], v[106:107], v[98:99]
	v_pk_mul_f32 v[108:109], v[108:109], v[100:101]
	v_pk_mul_f32 v[96:97], v[96:97], v[104:105]
	v_pk_mul_f32 v[94:95], v[94:95], v[102:103]
	v_pk_mul_f32 v[90:91], v[90:91], v[98:99]
	v_pk_mul_f32 v[92:93], v[92:93], v[100:101]
	v_pk_mul_f32 v[88:89], v[88:89], v[104:105]
	v_pk_mul_f32 v[86:87], v[86:87], v[102:103]
	v_pk_mul_f32 v[82:83], v[82:83], v[98:99]
	v_pk_mul_f32 v[84:85], v[84:85], v[100:101]
	v_pk_mul_f32 v[80:81], v[80:81], v[104:105]
	v_pk_mul_f32 v[78:79], v[78:79], v[102:103]
	v_pk_mul_f32 v[74:75], v[74:75], v[98:99]
	v_pk_mul_f32 v[76:77], v[76:77], v[100:101]
	s_waitcnt vmcnt(5)
; __device__ __forceinline__ unsigned cvt_pk_bf16(float lo, float hi) { unsigned r; asm volatile("v_cvt_pk_bf16_f32 %0, %1, %2" : "=v"(r) : "v"(lo), "v"(hi)); return r; }
;     __device__ __forceinline__ void operator()(const f32x4 (&acc)[2][2][4][2], const Unit& u, int wr, int wc, int fr, int fq) const {
;     ...
;                     if constexpr (OUT_DELTA) { const f32x4 d0 = g0 * acc[ai][bj][m][0], d1 = g1 * acc[ai][bj][m][1];
;                         u32x4 w; w.x = cvt_pk_bf16(d0[0], d0[1]); w.y = cvt_pk_bf16(d0[2], d0[3]); w.z = cvt_pk_bf16(d1[0], d1[1]); w.w = cvt_pk_bf16(d1[2], d1[3]);
;                         *(u32x4*)(dbuf + off) = w;
;                         o0 = x0 + (f32x4){__builtin_bit_cast(float, w.x << 16), __builtin_bit_cast(float, w.x & 0xffff0000u), __builtin_bit_cast(float, w.y << 16), __builtin_bit_cast(float, w.y & 0xffff0000u)};
;                         o1 = x1 + (f32x4){__builtin_bit_cast(float, w.z << 16), __builtin_bit_cast(float, w.z & 0xffff0000u), __builtin_bit_cast(float, w.w << 16), __builtin_bit_cast(float, w.w & 0xffff0000u)}; }
;                     else { o0 = x0 + g0 * acc[ai][bj][m][0]; o1 = x1 + g1 * acc[ai][bj][m][1]; *(f32x4*)(out + off) = o0; *(f32x4*)(out + off + 4) = o1; }
;                     if (Hn) { const f32x4 h0 = o0 * G0, h1 = o1 * G1;
;                         u32x4 w; w.x = cvt_pk_bf16(h0[0], h0[1]); w.y = cvt_pk_bf16(h0[2], h0[3]); w.z = cvt_pk_bf16(h1[0], h1[1]); w.w = cvt_pk_bf16(h1[2], h1[3]);
;                         *(u32x4*)(Hn + off) = w;
;                         ssq[ai][m] += ((o0[0] * o0[0] + o0[1] * o0[1]) + (o0[2] * o0[2] + o0[3] * o0[3])) + ((o1[0] * o1[0] + o1[1] * o1[1]) + (o1[2] * o1[2] + o1[3] * o1[3])); } }
	v_pk_mul_f32 v[58:59], v[58:59], v[26:27]
	s_waitcnt vmcnt(4)
	v_pk_mul_f32 v[72:73], v[72:73], v[32:33]
	v_pk_mul_f32 v[70:71], v[70:71], v[30:31]
	v_pk_mul_f32 v[64:65], v[64:65], v[32:33]
	v_pk_mul_f32 v[62:63], v[62:63], v[30:31]
	s_waitcnt vmcnt(0)
	v_pk_add_f32 v[146:147], v[184:185], 1.0 op_sel_hi:[1,0]
	v_pk_add_f32 v[160:161], v[182:183], 1.0 op_sel_hi:[1,0]
	v_pk_mul_f32 v[150:151], v[154:155], v[146:147]
	v_pk_add_f32 v[146:147], v[180:181], 1.0 op_sel_hi:[1,0]
	v_pk_mul_f32 v[152:153], v[152:153], v[160:161]
	v_pk_mul_f32 v[154:155], v[158:159], v[146:147]
	v_lshl_add_u32 v146, s29, 8, v207
	v_ashrrev_i32_e32 v147, 31, v146
	v_lshlrev_b64 v[184:185], 11, v[146:147]
	v_lshl_add_u64 v[186:187], v[184:185], 0, v[148:149]
	v_pk_add_f32 v[160:161], v[178:179], 1.0 op_sel_hi:[1,0]
	v_lshl_add_u64 v[178:179], v[186:187], 2, s[44:45]
	v_pk_mul_f32 v[156:157], v[156:157], v[160:161]
	global_load_dwordx4 v[158:161], v[178:179], off nt
	global_load_dwordx4 v[180:183], v[178:179], off offset:16 nt
	v_cvt_pk_bf16_f32 v138, v142, v143
	v_lshlrev_b64 v[142:143], 1, v[186:187]
	v_cvt_pk_bf16_f32 v139, v144, v145
	v_cvt_pk_bf16_f32 v140, v140, v141
	v_cvt_pk_bf16_f32 v141, v188, v189
	v_lshl_add_u64 v[144:145], s[90:91], 0, v[142:143]
	global_store_dwordx4 v[144:145], v[138:141], off
	v_lshlrev_b32_e32 v144, 16, v140
	v_and_b32_e32 v145, 0xffff0000, v140
	v_lshlrev_b32_e32 v140, 16, v141
	v_and_b32_e32 v141, 0xffff0000, v141
	v_lshl_add_u64 v[142:143], s[96:97], 0, v[142:143]
	v_pk_mul_f32 v[60:61], v[60:61], v[28:29]
	v_pk_mul_f32 v[56:57], v[56:57], v[32:33]
	v_pk_mul_f32 v[54:55], v[54:55], v[30:31]
	v_pk_mul_f32 v[50:51], v[50:51], v[26:27]
	v_pk_mul_f32 v[52:53], v[52:53], v[28:29]
	v_pk_mul_f32 v[48:49], v[48:49], v[32:33]
	v_pk_mul_f32 v[46:47], v[46:47], v[30:31]
	v_pk_mul_f32 v[42:43], v[42:43], v[26:27]
	v_pk_mul_f32 v[44:45], v[44:45], v[28:29]
	v_pk_mul_f32 v[40:41], v[40:41], v[32:33]
	v_pk_mul_f32 v[38:39], v[38:39], v[30:31]
	v_pk_mul_f32 v[34:35], v[34:35], v[26:27]
	v_pk_mul_f32 v[36:37], v[36:37], v[28:29]
	v_pk_mul_f32 v[24:25], v[24:25], v[32:33]
	v_pk_mul_f32 v[22:23], v[22:23], v[30:31]
	v_pk_mul_f32 v[18:19], v[18:19], v[26:27]
	v_pk_mul_f32 v[20:21], v[20:21], v[28:29]
	v_pk_mul_f32 v[16:17], v[16:17], v[32:33]
	v_pk_mul_f32 v[14:15], v[14:15], v[30:31]
	v_pk_mul_f32 v[10:11], v[10:11], v[26:27]
	v_pk_mul_f32 v[12:13], v[12:13], v[28:29]
	v_pk_mul_f32 v[8:9], v[8:9], v[32:33]
	v_pk_mul_f32 v[6:7], v[6:7], v[30:31]
	v_pk_mul_f32 v[2:3], v[2:3], v[26:27]
	v_pk_mul_f32 v[4:5], v[4:5], v[28:29]
	s_waitcnt vmcnt(1)
	v_pk_add_f32 v[182:183], v[182:183], v[140:141]
	v_lshlrev_b32_e32 v140, 16, v138
	v_and_b32_e32 v141, 0xffff0000, v138
	v_lshlrev_b32_e32 v138, 16, v139
	v_and_b32_e32 v139, 0xffff0000, v139
	v_pk_add_f32 v[158:159], v[158:159], v[140:141]
	v_pk_add_f32 v[160:161], v[160:161], v[138:139]
	v_pk_mul_f32 v[138:139], v[200:201], v[158:159]
	v_pk_add_f32 v[144:145], v[180:181], v[144:145]
	v_pk_mul_f32 v[140:141], v[198:199], v[160:161]
	v_cvt_pk_bf16_f32 v138, v138, v139
	v_pk_mul_f32 v[180:181], v[202:203], v[182:183]
	v_cvt_pk_bf16_f32 v139, v140, v141
	v_pk_mul_f32 v[186:187], v[204:205], v[144:145]
	s_nop 0
	v_cvt_pk_bf16_f32 v140, v186, v187
	v_cvt_pk_bf16_f32 v141, v180, v181
	global_store_dwordx4 v[142:143], v[138:141], off
	s_nop 1
	v_mul_f32_e32 v138, v159, v159
	v_mul_f32_e32 v139, v161, v161
	v_fmac_f32_e32 v138, v158, v158
	v_fmac_f32_e32 v139, v160, v160
	v_add_f32_e32 v138, v138, v139
	v_mul_f32_e32 v139, v145, v145
	v_mul_f32_e32 v140, v183, v183
	v_fmac_f32_e32 v139, v144, v144
	v_fmac_f32_e32 v140, v182, v182
	v_add_f32_e32 v139, v139, v140
	v_add_f32_e32 v211, v138, v139
	v_or_b32_e32 v138, 16, v146
	v_ashrrev_i32_e32 v139, 31, v138
	v_lshlrev_b64 v[140:141], 11, v[138:139]
	v_lshl_add_u64 v[180:181], v[140:141], 0, v[148:149]
	v_lshl_add_u64 v[138:139], v[180:181], 2, s[44:45]
	global_load_dwordx4 v[142:145], v[138:139], off nt
	global_load_dwordx4 v[158:161], v[138:139], off offset:16 nt
	v_lshlrev_b64 v[180:181], 1, v[180:181]
	v_cvt_pk_bf16_f32 v134, v134, v135
	v_cvt_pk_bf16_f32 v135, v136, v137
	v_cvt_pk_bf16_f32 v136, v130, v131
	v_cvt_pk_bf16_f32 v137, v132, v133
	v_lshl_add_u64 v[130:131], s[90:91], 0, v[180:181]
	global_store_dwordx4 v[130:131], v[134:137], off
	v_lshlrev_b32_e32 v132, 16, v136
	v_and_b32_e32 v133, 0xffff0000, v136
	v_lshlrev_b32_e32 v130, 16, v137
	v_and_b32_e32 v131, 0xffff0000, v137
	v_lshlrev_b32_e32 v136, 16, v134
	v_and_b32_e32 v137, 0xffff0000, v134
	v_lshlrev_b32_e32 v134, 16, v135
	v_and_b32_e32 v135, 0xffff0000, v135
	s_waitcnt vmcnt(2)
	v_pk_add_f32 v[134:135], v[144:145], v[134:135]
	s_waitcnt vmcnt(1)
	v_pk_add_f32 v[130:131], v[160:161], v[130:131]
	v_pk_add_f32 v[136:137], v[142:143], v[136:137]
	v_pk_add_f32 v[132:133], v[158:159], v[132:133]
	v_pk_mul_f32 v[144:145], v[198:199], v[134:135]
	v_pk_mul_f32 v[142:143], v[200:201], v[136:137]
	v_pk_mul_f32 v[158:159], v[202:203], v[130:131]
	v_pk_mul_f32 v[160:161], v[204:205], v[132:133]
	v_cvt_pk_bf16_f32 v142, v142, v143
	v_cvt_pk_bf16_f32 v143, v144, v145
	s_nop 0
	v_cvt_pk_bf16_f32 v144, v160, v161
	v_cvt_pk_bf16_f32 v145, v158, v159
	v_lshl_add_u64 v[158:159], s[96:97], 0, v[180:181]
	global_store_dwordx4 v[158:159], v[142:145], off
	s_nop 1
	v_or_b32_e32 v142, 32, v146
	v_ashrrev_i32_e32 v143, 31, v142
	v_lshlrev_b64 v[144:145], 11, v[142:143]
	v_lshl_add_u64 v[186:187], v[144:145], 0, v[148:149]
	v_lshl_add_u64 v[142:143], v[186:187], 2, s[44:45]
	global_load_dwordx4 v[158:161], v[142:143], off nt
	global_load_dwordx4 v[180:183], v[142:143], off offset:16 nt
	v_lshlrev_b64 v[186:187], 1, v[186:187]
	v_cvt_pk_bf16_f32 v126, v126, v127
	v_cvt_pk_bf16_f32 v127, v128, v129
	v_cvt_pk_bf16_f32 v128, v122, v123
	v_cvt_pk_bf16_f32 v129, v124, v125
	v_lshl_add_u64 v[122:123], s[90:91], 0, v[186:187]
	global_store_dwordx4 v[122:123], v[126:129], off
	v_lshlrev_b32_e32 v124, 16, v128
	v_and_b32_e32 v125, 0xffff0000, v128
	v_lshlrev_b32_e32 v122, 16, v129
	v_and_b32_e32 v123, 0xffff0000, v129
	v_lshlrev_b32_e32 v128, 16, v126
	v_and_b32_e32 v129, 0xffff0000, v126
	v_lshlrev_b32_e32 v126, 16, v127
	v_and_b32_e32 v127, 0xffff0000, v127
	s_waitcnt vmcnt(2)
; __device__ __forceinline__ unsigned cvt_pk_bf16(float lo, float hi) { unsigned r; asm volatile("v_cvt_pk_bf16_f32 %0, %1, %2" : "=v"(r) : "v"(lo), "v"(hi)); return r; }
;     __device__ __forceinline__ void operator()(const f32x4 (&acc)[2][2][4][2], const Unit& u, int wr, int wc, int fr, int fq) const {
;     ...
;                 for (int m = 0; m < 4; ++m) { const size_t off = (size_t)(row0 + ai * HALF + m * 16) * 2048 + col0 + bj * HALF;
;                     f32x4 x0 = __builtin_nontemporal_load((const f32x4*)(base + off)), x1 = __builtin_nontemporal_load((const f32x4*)(base + off + 4));
;                     if constexpr (HAS_DIN) { const u32x4 dw = __builtin_nontemporal_load((const u32x4*)(dbuf + off));
;                         x0 += (f32x4){__builtin_bit_cast(float, dw.x << 16), __builtin_bit_cast(float, dw.x & 0xffff0000u), __builtin_bit_cast(float, dw.y << 16), __builtin_bit_cast(float, dw.y & 0xffff0000u)};
;                         x1 += (f32x4){__builtin_bit_cast(float, dw.z << 16), __builtin_bit_cast(float, dw.z & 0xffff0000u), __builtin_bit_cast(float, dw.w << 16), __builtin_bit_cast(float, dw.w & 0xffff0000u)}; }
;                     f32x4 o0, o1;
;                     if constexpr (OUT_DELTA) { const f32x4 d0 = g0 * acc[ai][bj][m][0], d1 = g1 * acc[ai][bj][m][1];
;                         u32x4 w; w.x = cvt_pk_bf16(d0[0], d0[1]); w.y = cvt_pk_bf16(d0[2], d0[3]); w.z = cvt_pk_bf16(d1[0], d1[1]); w.w = cvt_pk_bf16(d1[2], d1[3]);
;                         *(u32x4*)(dbuf + off) = w;
;                         o0 = x0 + (f32x4){__builtin_bit_cast(float, w.x << 16), __builtin_bit_cast(float, w.x & 0xffff0000u), __builtin_bit_cast(float, w.y << 16), __builtin_bit_cast(float, w.y & 0xffff0000u)};
;                         o1 = x1 + (f32x4){__builtin_bit_cast(float, w.z << 16), __builtin_bit_cast(float, w.z & 0xffff0000u), __builtin_bit_cast(float, w.w << 16), __builtin_bit_cast(float, w.w & 0xffff0000u)}; }
;                     else { o0 = x0 + g0 * acc[ai][bj][m][0]; o1 = x1 + g1 * acc[ai][bj][m][1]; *(f32x4*)(out + off) = o0; *(f32x4*)(out + off + 4) = o1; }
;                     if (Hn) { const f32x4 h0 = o0 * G0, h1 = o1 * G1;
;                         u32x4 w; w.x = cvt_pk_bf16(h0[0], h0[1]); w.y = cvt_pk_bf16(h0[2], h0[3]); w.z = cvt_pk_bf16(h1[0], h1[1]); w.w = cvt_pk_bf16(h1[2], h1[3]);
;                         *(u32x4*)(Hn + off) = w;
	v_pk_add_f32 v[126:127], v[160:161], v[126:127]
	s_waitcnt vmcnt(1)
	v_pk_add_f32 v[122:123], v[182:183], v[122:123]
	v_pk_add_f32 v[128:129], v[158:159], v[128:129]
	v_pk_add_f32 v[124:125], v[180:181], v[124:125]
	v_pk_mul_f32 v[160:161], v[198:199], v[126:127]
	v_pk_mul_f32 v[158:159], v[200:201], v[128:129]
	v_pk_mul_f32 v[180:181], v[202:203], v[122:123]
	v_pk_mul_f32 v[182:183], v[204:205], v[124:125]
	v_cvt_pk_bf16_f32 v158, v158, v159
	v_cvt_pk_bf16_f32 v159, v160, v161
	s_nop 0
	v_cvt_pk_bf16_f32 v160, v182, v183
	v_cvt_pk_bf16_f32 v161, v180, v181
	v_lshl_add_u64 v[180:181], s[96:97], 0, v[186:187]
	global_store_dwordx4 v[180:181], v[158:161], off
	s_nop 1
	v_or_b32_e32 v158, 48, v146
	v_ashrrev_i32_e32 v159, 31, v158
	v_lshlrev_b64 v[160:161], 11, v[158:159]
	v_lshl_add_u64 v[190:191], v[160:161], 0, v[148:149]
	v_lshl_add_u64 v[158:159], v[190:191], 2, s[44:45]
	global_load_dwordx4 v[180:183], v[158:159], off nt
	global_load_dwordx4 v[186:189], v[158:159], off offset:16 nt
	v_lshlrev_b64 v[190:191], 1, v[190:191]
	v_cvt_pk_bf16_f32 v118, v118, v119
	v_cvt_pk_bf16_f32 v119, v120, v121
	v_cvt_pk_bf16_f32 v120, v114, v115
	v_cvt_pk_bf16_f32 v121, v116, v117
	v_lshl_add_u64 v[114:115], s[90:91], 0, v[190:191]
	global_store_dwordx4 v[114:115], v[118:121], off
	v_lshlrev_b32_e32 v116, 16, v120
	v_and_b32_e32 v117, 0xffff0000, v120
	v_lshlrev_b32_e32 v114, 16, v121
	v_and_b32_e32 v115, 0xffff0000, v121
	v_lshlrev_b32_e32 v120, 16, v118
	v_and_b32_e32 v121, 0xffff0000, v118
	v_lshlrev_b32_e32 v118, 16, v119
	v_and_b32_e32 v119, 0xffff0000, v119
	s_waitcnt vmcnt(2)
	v_pk_add_f32 v[118:119], v[182:183], v[118:119]
	s_waitcnt vmcnt(1)
	v_pk_add_f32 v[114:115], v[188:189], v[114:115]
	v_pk_add_f32 v[120:121], v[180:181], v[120:121]
	v_pk_add_f32 v[116:117], v[186:187], v[116:117]
	v_pk_mul_f32 v[182:183], v[198:199], v[118:119]
	v_pk_mul_f32 v[180:181], v[200:201], v[120:121]
	v_pk_mul_f32 v[186:187], v[202:203], v[114:115]
	v_pk_mul_f32 v[188:189], v[204:205], v[116:117]
	v_cvt_pk_bf16_f32 v180, v180, v181
	v_cvt_pk_bf16_f32 v181, v182, v183
	s_nop 0
	v_cvt_pk_bf16_f32 v182, v188, v189
	v_cvt_pk_bf16_f32 v183, v186, v187
	v_lshl_add_u64 v[186:187], s[96:97], 0, v[190:191]
	global_store_dwordx4 v[186:187], v[180:183], off
	s_nop 1
	v_lshl_add_u64 v[182:183], v[184:185], 0, s[4:5]
	v_lshl_add_u64 v[194:195], v[182:183], 0, v[148:149]
	v_lshl_add_u64 v[180:181], v[194:195], 2, s[44:45]
	global_load_dwordx4 v[186:189], v[180:181], off nt
	global_load_dwordx4 v[190:193], v[180:181], off offset:16 nt
	v_lshlrev_b64 v[194:195], 1, v[194:195]
	v_cvt_pk_bf16_f32 v110, v110, v111
	v_cvt_pk_bf16_f32 v111, v112, v113
	v_cvt_pk_bf16_f32 v112, v106, v107
	v_cvt_pk_bf16_f32 v113, v108, v109
	v_lshl_add_u64 v[106:107], s[90:91], 0, v[194:195]
	global_store_dwordx4 v[106:107], v[110:113], off
	v_lshlrev_b32_e32 v108, 16, v112
	v_and_b32_e32 v109, 0xffff0000, v112
	v_lshlrev_b32_e32 v106, 16, v113
	v_and_b32_e32 v107, 0xffff0000, v113
	v_lshlrev_b32_e32 v112, 16, v110
	v_and_b32_e32 v113, 0xffff0000, v110
	v_lshlrev_b32_e32 v110, 16, v111
	v_and_b32_e32 v111, 0xffff0000, v111
	s_mov_b64 s[4:5], 0x48000
	s_waitcnt vmcnt(2)
	v_pk_add_f32 v[110:111], v[188:189], v[110:111]
	s_waitcnt vmcnt(1)
	v_pk_add_f32 v[106:107], v[192:193], v[106:107]
	v_pk_add_f32 v[112:113], v[186:187], v[112:113]
	v_pk_add_f32 v[108:109], v[190:191], v[108:109]
	v_pk_mul_f32 v[188:189], v[198:199], v[110:111]
	v_pk_mul_f32 v[186:187], v[200:201], v[112:113]
	v_pk_mul_f32 v[190:191], v[202:203], v[106:107]
	v_pk_mul_f32 v[192:193], v[204:205], v[108:109]
	v_cvt_pk_bf16_f32 v186, v186, v187
	v_cvt_pk_bf16_f32 v187, v188, v189
	s_nop 0
	v_cvt_pk_bf16_f32 v188, v192, v193
	v_cvt_pk_bf16_f32 v189, v190, v191
	v_lshl_add_u64 v[190:191], s[96:97], 0, v[194:195]
	global_store_dwordx4 v[190:191], v[186:189], off
	s_nop 1
	v_lshl_add_u64 v[188:189], v[184:185], 0, s[4:5]
	v_lshl_add_u64 v[212:213], v[188:189], 0, v[148:149]
	v_lshl_add_u64 v[186:187], v[212:213], 2, s[44:45]
	global_load_dwordx4 v[190:193], v[186:187], off nt
	global_load_dwordx4 v[194:197], v[186:187], off offset:16 nt
	v_lshlrev_b64 v[212:213], 1, v[212:213]
	v_cvt_pk_bf16_f32 v94, v94, v95
	v_cvt_pk_bf16_f32 v95, v96, v97
	v_cvt_pk_bf16_f32 v96, v90, v91
	v_cvt_pk_bf16_f32 v97, v92, v93
	v_lshl_add_u64 v[90:91], s[90:91], 0, v[212:213]
	global_store_dwordx4 v[90:91], v[94:97], off
	v_lshlrev_b32_e32 v92, 16, v96
	v_and_b32_e32 v93, 0xffff0000, v96
	v_lshlrev_b32_e32 v90, 16, v97
	v_and_b32_e32 v91, 0xffff0000, v97
	v_lshlrev_b32_e32 v96, 16, v94
	v_and_b32_e32 v97, 0xffff0000, v94
	v_lshlrev_b32_e32 v94, 16, v95
	v_and_b32_e32 v95, 0xffff0000, v95
	s_mov_b64 s[4:5], 0x50000
	s_waitcnt vmcnt(2)
	v_pk_add_f32 v[94:95], v[192:193], v[94:95]
	s_waitcnt vmcnt(1)
	v_pk_add_f32 v[90:91], v[196:197], v[90:91]
	v_pk_add_f32 v[96:97], v[190:191], v[96:97]
	v_pk_add_f32 v[92:93], v[194:195], v[92:93]
	v_pk_mul_f32 v[192:193], v[198:199], v[94:95]
	v_pk_mul_f32 v[190:191], v[200:201], v[96:97]
	v_pk_mul_f32 v[194:195], v[202:203], v[90:91]
	v_pk_mul_f32 v[196:197], v[204:205], v[92:93]
	v_cvt_pk_bf16_f32 v190, v190, v191
	v_cvt_pk_bf16_f32 v191, v192, v193
	s_nop 0
	v_cvt_pk_bf16_f32 v192, v196, v197
	v_cvt_pk_bf16_f32 v193, v194, v195
	v_lshl_add_u64 v[194:195], s[96:97], 0, v[212:213]
	global_store_dwordx4 v[194:195], v[190:193], off
	s_nop 1
	v_lshl_add_u64 v[192:193], v[184:185], 0, s[4:5]
	v_lshl_add_u64 v[220:221], v[192:193], 0, v[148:149]
	v_lshl_add_u64 v[190:191], v[220:221], 2, s[44:45]
	global_load_dwordx4 v[194:197], v[190:191], off nt
	global_load_dwordx4 v[212:215], v[190:191], off offset:16 nt
	v_lshlrev_b64 v[220:221], 1, v[220:221]
	v_cvt_pk_bf16_f32 v86, v86, v87
	v_cvt_pk_bf16_f32 v87, v88, v89
	v_cvt_pk_bf16_f32 v88, v82, v83
	v_cvt_pk_bf16_f32 v89, v84, v85
	v_lshl_add_u64 v[82:83], s[90:91], 0, v[220:221]
	global_store_dwordx4 v[82:83], v[86:89], off
	v_lshlrev_b32_e32 v84, 16, v88
	v_and_b32_e32 v85, 0xffff0000, v88
	v_lshlrev_b32_e32 v82, 16, v89
	v_and_b32_e32 v83, 0xffff0000, v89
	v_lshlrev_b32_e32 v88, 16, v86
	v_and_b32_e32 v89, 0xffff0000, v86
	v_lshlrev_b32_e32 v86, 16, v87
	v_and_b32_e32 v87, 0xffff0000, v87
	s_mov_b64 s[4:5], 0x58000
	s_waitcnt vmcnt(2)
; __device__ __forceinline__ unsigned cvt_pk_bf16(float lo, float hi) { unsigned r; asm volatile("v_cvt_pk_bf16_f32 %0, %1, %2" : "=v"(r) : "v"(lo), "v"(hi)); return r; }
;     __device__ __forceinline__ void operator()(const f32x4 (&acc)[2][2][4][2], const Unit& u, int wr, int wc, int fr, int fq) const {
;     ...
;                 for (int m = 0; m < 4; ++m) { const size_t off = (size_t)(row0 + ai * HALF + m * 16) * 2048 + col0 + bj * HALF;
;                     f32x4 x0 = __builtin_nontemporal_load((const f32x4*)(base + off)), x1 = __builtin_nontemporal_load((const f32x4*)(base + off + 4));
;                     if constexpr (HAS_DIN) { const u32x4 dw = __builtin_nontemporal_load((const u32x4*)(dbuf + off));
;                         x0 += (f32x4){__builtin_bit_cast(float, dw.x << 16), __builtin_bit_cast(float, dw.x & 0xffff0000u), __builtin_bit_cast(float, dw.y << 16), __builtin_bit_cast(float, dw.y & 0xffff0000u)};
;                         x1 += (f32x4){__builtin_bit_cast(float, dw.z << 16), __builtin_bit_cast(float, dw.z & 0xffff0000u), __builtin_bit_cast(float, dw.w << 16), __builtin_bit_cast(float, dw.w & 0xffff0000u)}; }
;                     f32x4 o0, o1;
;                     if constexpr (OUT_DELTA) { const f32x4 d0 = g0 * acc[ai][bj][m][0], d1 = g1 * acc[ai][bj][m][1];
;                         u32x4 w; w.x = cvt_pk_bf16(d0[0], d0[1]); w.y = cvt_pk_bf16(d0[2], d0[3]); w.z = cvt_pk_bf16(d1[0], d1[1]); w.w = cvt_pk_bf16(d1[2], d1[3]);
;                         *(u32x4*)(dbuf + off) = w;
;                         o0 = x0 + (f32x4){__builtin_bit_cast(float, w.x << 16), __builtin_bit_cast(float, w.x & 0xffff0000u), __builtin_bit_cast(float, w.y << 16), __builtin_bit_cast(float, w.y & 0xffff0000u)};
;                         o1 = x1 + (f32x4){__builtin_bit_cast(float, w.z << 16), __builtin_bit_cast(float, w.z & 0xffff0000u), __builtin_bit_cast(float, w.w << 16), __builtin_bit_cast(float, w.w & 0xffff0000u)}; }
;                     else { o0 = x0 + g0 * acc[ai][bj][m][0]; o1 = x1 + g1 * acc[ai][bj][m][1]; *(f32x4*)(out + off) = o0; *(f32x4*)(out + off + 4) = o1; }
;                     if (Hn) { const f32x4 h0 = o0 * G0, h1 = o1 * G1;
;                         u32x4 w; w.x = cvt_pk_bf16(h0[0], h0[1]); w.y = cvt_pk_bf16(h0[2], h0[3]); w.z = cvt_pk_bf16(h1[0], h1[1]); w.w = cvt_pk_bf16(h1[2], h1[3]);
;                         *(u32x4*)(Hn + off) = w;
	v_pk_add_f32 v[86:87], v[196:197], v[86:87]
	s_waitcnt vmcnt(1)
	v_pk_add_f32 v[82:83], v[214:215], v[82:83]
	v_pk_add_f32 v[88:89], v[194:195], v[88:89]
	v_pk_add_f32 v[84:85], v[212:213], v[84:85]
	v_pk_mul_f32 v[196:197], v[198:199], v[86:87]
	v_pk_mul_f32 v[194:195], v[200:201], v[88:89]
	v_pk_mul_f32 v[212:213], v[202:203], v[82:83]
	v_pk_mul_f32 v[214:215], v[204:205], v[84:85]
	v_cvt_pk_bf16_f32 v194, v194, v195
	v_cvt_pk_bf16_f32 v195, v196, v197
	s_nop 0
	v_cvt_pk_bf16_f32 v196, v214, v215
	v_cvt_pk_bf16_f32 v197, v212, v213
	v_lshl_add_u64 v[212:213], s[96:97], 0, v[220:221]
	global_store_dwordx4 v[212:213], v[194:197], off
	s_nop 1
	v_lshl_add_u64 v[196:197], v[184:185], 0, s[4:5]
	v_lshl_add_u64 v[224:225], v[196:197], 0, v[148:149]
	v_lshl_add_u64 v[194:195], v[224:225], 2, s[44:45]
	global_load_dwordx4 v[212:215], v[194:195], off nt
	global_load_dwordx4 v[220:223], v[194:195], off offset:16 nt
	v_lshlrev_b64 v[102:103], 1, v[224:225]
	v_cvt_pk_bf16_f32 v78, v78, v79
	v_cvt_pk_bf16_f32 v79, v80, v81
	v_cvt_pk_bf16_f32 v80, v74, v75
	v_cvt_pk_bf16_f32 v81, v76, v77
	v_lshl_add_u64 v[74:75], s[90:91], 0, v[102:103]
	global_store_dwordx4 v[74:75], v[78:81], off
	v_lshlrev_b32_e32 v76, 16, v80
	v_and_b32_e32 v77, 0xffff0000, v80
	v_lshlrev_b32_e32 v74, 16, v81
	v_and_b32_e32 v75, 0xffff0000, v81
	v_lshlrev_b32_e32 v80, 16, v78
	v_and_b32_e32 v81, 0xffff0000, v78
	v_lshlrev_b32_e32 v78, 16, v79
	v_and_b32_e32 v79, 0xffff0000, v79
	v_lshl_add_u64 v[102:103], s[96:97], 0, v[102:103]
	v_or_b32_e32 v148, 0x80, v148
	s_waitcnt vmcnt(2)
	v_pk_add_f32 v[78:79], v[214:215], v[78:79]
	v_pk_add_f32 v[80:81], v[212:213], v[80:81]
	s_waitcnt vmcnt(1)
	v_pk_add_f32 v[74:75], v[222:223], v[74:75]
	v_pk_add_f32 v[76:77], v[220:221], v[76:77]
	v_pk_mul_f32 v[100:101], v[198:199], v[78:79]
	v_pk_mul_f32 v[98:99], v[200:201], v[80:81]
	v_pk_mul_f32 v[104:105], v[202:203], v[74:75]
	v_pk_mul_f32 v[198:199], v[204:205], v[76:77]
	v_cvt_pk_bf16_f32 v98, v98, v99
	v_cvt_pk_bf16_f32 v99, v100, v101
	s_nop 0
	v_cvt_pk_bf16_f32 v100, v198, v199
	v_cvt_pk_bf16_f32 v101, v104, v105
	global_store_dwordx4 v[102:103], v[98:101], off
	global_load_dwordx4 v[100:103], v[178:179], off offset:512 nt
	global_load_dwordx4 v[198:201], v[178:179], off offset:528 nt
	v_lshl_add_u64 v[98:99], v[184:185], 0, v[148:149]
	v_pk_mul_f32 v[104:105], v[68:69], v[28:29]
	v_pk_mul_f32 v[68:69], v[66:67], v[26:27]
	v_cvt_pk_bf16_f32 v66, v70, v71
	v_cvt_pk_bf16_f32 v67, v72, v73
	s_nop 0
	v_cvt_pk_bf16_f32 v68, v68, v69
	v_cvt_pk_bf16_f32 v69, v104, v105
	v_lshlrev_b64 v[104:105], 1, v[98:99]
	v_lshl_add_u64 v[70:71], s[90:91], 0, v[104:105]
	global_store_dwordx4 v[70:71], v[66:69], off
	v_lshlrev_b32_e32 v72, 16, v68
	v_and_b32_e32 v73, 0xffff0000, v68
	v_lshlrev_b32_e32 v68, 16, v69
	v_and_b32_e32 v69, 0xffff0000, v69
	s_waitcnt vmcnt(1)
	v_pk_add_f32 v[70:71], v[200:201], v[68:69]
	v_lshlrev_b32_e32 v68, 16, v66
	v_and_b32_e32 v69, 0xffff0000, v66
	v_lshlrev_b32_e32 v66, 16, v67
	v_and_b32_e32 v67, 0xffff0000, v67
	v_pk_add_f32 v[98:99], v[102:103], v[66:67]
	v_pk_add_f32 v[100:101], v[100:101], v[68:69]
	v_pk_add_f32 v[72:73], v[198:199], v[72:73]
	v_pk_mul_f32 v[68:69], v[150:151], v[98:99]
	v_pk_mul_f32 v[66:67], v[152:153], v[100:101]
	v_pk_mul_f32 v[102:103], v[154:155], v[70:71]
	v_pk_mul_f32 v[178:179], v[156:157], v[72:73]
	v_cvt_pk_bf16_f32 v66, v66, v67
	v_cvt_pk_bf16_f32 v67, v68, v69
	s_nop 0
	v_cvt_pk_bf16_f32 v68, v178, v179
	v_cvt_pk_bf16_f32 v69, v102, v103
	v_lshl_add_u64 v[102:103], s[96:97], 0, v[104:105]
	global_store_dwordx4 v[102:103], v[66:69], off
	s_nop 1
	v_mul_f32_e32 v66, v101, v101
	v_mul_f32_e32 v67, v99, v99
	v_fmac_f32_e32 v66, v100, v100
	v_fmac_f32_e32 v67, v98, v98
	v_add_f32_e32 v66, v66, v67
	v_mul_f32_e32 v67, v73, v73
	v_mul_f32_e32 v68, v71, v71
	v_fmac_f32_e32 v67, v72, v72
	v_fmac_f32_e32 v68, v70, v70
	v_add_f32_e32 v67, v67, v68
	global_load_dwordx4 v[68:71], v[138:139], off offset:512 nt
	global_load_dwordx4 v[98:101], v[138:139], off offset:528 nt
	v_lshl_add_u64 v[72:73], v[140:141], 0, v[148:149]
	v_lshlrev_b64 v[72:73], 1, v[72:73]
	v_cvt_pk_bf16_f32 v62, v62, v63
	v_cvt_pk_bf16_f32 v63, v64, v65
	v_cvt_pk_bf16_f32 v64, v58, v59
	v_cvt_pk_bf16_f32 v65, v60, v61
	v_lshl_add_u64 v[58:59], s[90:91], 0, v[72:73]
	global_store_dwordx4 v[58:59], v[62:65], off
	v_lshlrev_b32_e32 v60, 16, v64
	v_and_b32_e32 v61, 0xffff0000, v64
	v_lshlrev_b32_e32 v58, 16, v65
	v_and_b32_e32 v59, 0xffff0000, v65
	v_lshlrev_b32_e32 v64, 16, v62
	v_and_b32_e32 v65, 0xffff0000, v62
	v_lshlrev_b32_e32 v62, 16, v63
	v_and_b32_e32 v63, 0xffff0000, v63
	v_lshl_add_u64 v[72:73], s[96:97], 0, v[72:73]
	v_add_f32_e32 v66, v66, v67
	v_add_f32_e32 v66, v211, v66
	s_waitcnt vmcnt(2)
	v_pk_add_f32 v[62:63], v[70:71], v[62:63]
	v_pk_add_f32 v[64:65], v[68:69], v[64:65]
	s_waitcnt vmcnt(1)
	v_pk_add_f32 v[58:59], v[100:101], v[58:59]
	v_pk_add_f32 v[60:61], v[98:99], v[60:61]
	v_pk_mul_f32 v[70:71], v[150:151], v[62:63]
	v_pk_mul_f32 v[68:69], v[152:153], v[64:65]
	v_pk_mul_f32 v[98:99], v[154:155], v[58:59]
	v_pk_mul_f32 v[100:101], v[156:157], v[60:61]
	v_cvt_pk_bf16_f32 v68, v68, v69
	v_cvt_pk_bf16_f32 v69, v70, v71
	s_nop 0
	v_cvt_pk_bf16_f32 v70, v100, v101
	v_cvt_pk_bf16_f32 v71, v98, v99
	global_store_dwordx4 v[72:73], v[68:71], off
	global_load_dwordx4 v[68:71], v[142:143], off offset:512 nt
	s_nop 0
	global_load_dwordx4 v[98:101], v[142:143], off offset:528 nt
	v_lshl_add_u64 v[72:73], v[144:145], 0, v[148:149]
	v_lshlrev_b64 v[72:73], 1, v[72:73]
	v_cvt_pk_bf16_f32 v54, v54, v55
	v_cvt_pk_bf16_f32 v55, v56, v57
	v_cvt_pk_bf16_f32 v56, v50, v51
	v_cvt_pk_bf16_f32 v57, v52, v53
	v_lshl_add_u64 v[50:51], s[90:91], 0, v[72:73]
	global_store_dwordx4 v[50:51], v[54:57], off
	v_lshlrev_b32_e32 v52, 16, v56
	v_and_b32_e32 v53, 0xffff0000, v56
	v_lshlrev_b32_e32 v50, 16, v57
	v_and_b32_e32 v51, 0xffff0000, v57
	v_lshlrev_b32_e32 v56, 16, v54
	v_and_b32_e32 v57, 0xffff0000, v54
	v_lshlrev_b32_e32 v54, 16, v55
	v_and_b32_e32 v55, 0xffff0000, v55
	v_lshl_add_u64 v[72:73], s[96:97], 0, v[72:73]
	s_waitcnt vmcnt(2)
; __device__ __forceinline__ unsigned cvt_pk_bf16(float lo, float hi) { unsigned r; asm volatile("v_cvt_pk_bf16_f32 %0, %1, %2" : "=v"(r) : "v"(lo), "v"(hi)); return r; }
;     __device__ __forceinline__ void operator()(const f32x4 (&acc)[2][2][4][2], const Unit& u, int wr, int wc, int fr, int fq) const {
;     ...
;                 for (int m = 0; m < 4; ++m) { const size_t off = (size_t)(row0 + ai * HALF + m * 16) * 2048 + col0 + bj * HALF;
;                     f32x4 x0 = __builtin_nontemporal_load((const f32x4*)(base + off)), x1 = __builtin_nontemporal_load((const f32x4*)(base + off + 4));
;                     if constexpr (HAS_DIN) { const u32x4 dw = __builtin_nontemporal_load((const u32x4*)(dbuf + off));
;                         x0 += (f32x4){__builtin_bit_cast(float, dw.x << 16), __builtin_bit_cast(float, dw.x & 0xffff0000u), __builtin_bit_cast(float, dw.y << 16), __builtin_bit_cast(float, dw.y & 0xffff0000u)};
;                         x1 += (f32x4){__builtin_bit_cast(float, dw.z << 16), __builtin_bit_cast(float, dw.z & 0xffff0000u), __builtin_bit_cast(float, dw.w << 16), __builtin_bit_cast(float, dw.w & 0xffff0000u)}; }
;                     f32x4 o0, o1;
;                     if constexpr (OUT_DELTA) { const f32x4 d0 = g0 * acc[ai][bj][m][0], d1 = g1 * acc[ai][bj][m][1];
;                         u32x4 w; w.x = cvt_pk_bf16(d0[0], d0[1]); w.y = cvt_pk_bf16(d0[2], d0[3]); w.z = cvt_pk_bf16(d1[0], d1[1]); w.w = cvt_pk_bf16(d1[2], d1[3]);
;                         *(u32x4*)(dbuf + off) = w;
;                         o0 = x0 + (f32x4){__builtin_bit_cast(float, w.x << 16), __builtin_bit_cast(float, w.x & 0xffff0000u), __builtin_bit_cast(float, w.y << 16), __builtin_bit_cast(float, w.y & 0xffff0000u)};
;                         o1 = x1 + (f32x4){__builtin_bit_cast(float, w.z << 16), __builtin_bit_cast(float, w.z & 0xffff0000u), __builtin_bit_cast(float, w.w << 16), __builtin_bit_cast(float, w.w & 0xffff0000u)}; }
;                     else { o0 = x0 + g0 * acc[ai][bj][m][0]; o1 = x1 + g1 * acc[ai][bj][m][1]; *(f32x4*)(out + off) = o0; *(f32x4*)(out + off + 4) = o1; }
;                     if (Hn) { const f32x4 h0 = o0 * G0, h1 = o1 * G1;
;                         u32x4 w; w.x = cvt_pk_bf16(h0[0], h0[1]); w.y = cvt_pk_bf16(h0[2], h0[3]); w.z = cvt_pk_bf16(h1[0], h1[1]); w.w = cvt_pk_bf16(h1[2], h1[3]);
;                         *(u32x4*)(Hn + off) = w;
	v_pk_add_f32 v[54:55], v[70:71], v[54:55]
	v_pk_add_f32 v[56:57], v[68:69], v[56:57]
	s_waitcnt vmcnt(1)
	v_pk_add_f32 v[50:51], v[100:101], v[50:51]
	v_pk_add_f32 v[52:53], v[98:99], v[52:53]
	v_pk_mul_f32 v[70:71], v[150:151], v[54:55]
	v_pk_mul_f32 v[68:69], v[152:153], v[56:57]
	v_pk_mul_f32 v[98:99], v[154:155], v[50:51]
	v_pk_mul_f32 v[100:101], v[156:157], v[52:53]
	v_cvt_pk_bf16_f32 v68, v68, v69
	v_cvt_pk_bf16_f32 v69, v70, v71
	s_nop 0
	v_cvt_pk_bf16_f32 v70, v100, v101
	v_cvt_pk_bf16_f32 v71, v98, v99
	global_store_dwordx4 v[72:73], v[68:71], off
	global_load_dwordx4 v[68:71], v[158:159], off offset:512 nt
	s_nop 0
	global_load_dwordx4 v[98:101], v[158:159], off offset:528 nt
	v_lshl_add_u64 v[72:73], v[160:161], 0, v[148:149]
	v_lshlrev_b64 v[72:73], 1, v[72:73]
	v_cvt_pk_bf16_f32 v46, v46, v47
	v_cvt_pk_bf16_f32 v47, v48, v49
	v_cvt_pk_bf16_f32 v48, v42, v43
	v_cvt_pk_bf16_f32 v49, v44, v45
	v_lshl_add_u64 v[42:43], s[90:91], 0, v[72:73]
	global_store_dwordx4 v[42:43], v[46:49], off
	v_lshlrev_b32_e32 v44, 16, v48
	v_and_b32_e32 v45, 0xffff0000, v48
	v_lshlrev_b32_e32 v42, 16, v49
	v_and_b32_e32 v43, 0xffff0000, v49
	v_lshlrev_b32_e32 v48, 16, v46
	v_and_b32_e32 v49, 0xffff0000, v46
	v_lshlrev_b32_e32 v46, 16, v47
	v_and_b32_e32 v47, 0xffff0000, v47
	v_lshl_add_u64 v[72:73], s[96:97], 0, v[72:73]
	s_waitcnt vmcnt(2)
	v_pk_add_f32 v[46:47], v[70:71], v[46:47]
	v_pk_add_f32 v[48:49], v[68:69], v[48:49]
	s_waitcnt vmcnt(1)
	v_pk_add_f32 v[42:43], v[100:101], v[42:43]
	v_pk_add_f32 v[44:45], v[98:99], v[44:45]
	v_pk_mul_f32 v[70:71], v[150:151], v[46:47]
	v_pk_mul_f32 v[68:69], v[152:153], v[48:49]
	v_pk_mul_f32 v[98:99], v[154:155], v[42:43]
	v_pk_mul_f32 v[100:101], v[156:157], v[44:45]
	v_cvt_pk_bf16_f32 v68, v68, v69
	v_cvt_pk_bf16_f32 v69, v70, v71
	s_nop 0
	v_cvt_pk_bf16_f32 v70, v100, v101
	v_cvt_pk_bf16_f32 v71, v98, v99
	global_store_dwordx4 v[72:73], v[68:71], off
	global_load_dwordx4 v[68:71], v[180:181], off offset:512 nt
	s_nop 0
	global_load_dwordx4 v[98:101], v[180:181], off offset:528 nt
	v_lshl_add_u64 v[72:73], v[182:183], 0, v[148:149]
	v_lshlrev_b64 v[72:73], 1, v[72:73]
	v_cvt_pk_bf16_f32 v38, v38, v39
	v_cvt_pk_bf16_f32 v39, v40, v41
	v_cvt_pk_bf16_f32 v40, v34, v35
	v_cvt_pk_bf16_f32 v41, v36, v37
	v_lshl_add_u64 v[34:35], s[90:91], 0, v[72:73]
	global_store_dwordx4 v[34:35], v[38:41], off
	v_lshlrev_b32_e32 v36, 16, v40
	v_and_b32_e32 v37, 0xffff0000, v40
	v_lshlrev_b32_e32 v34, 16, v41
	v_and_b32_e32 v35, 0xffff0000, v41
	v_lshlrev_b32_e32 v40, 16, v38
	v_and_b32_e32 v41, 0xffff0000, v38
	v_lshlrev_b32_e32 v38, 16, v39
	v_and_b32_e32 v39, 0xffff0000, v39
	v_lshl_add_u64 v[72:73], s[96:97], 0, v[72:73]
	s_waitcnt vmcnt(2)
	v_pk_add_f32 v[38:39], v[70:71], v[38:39]
	v_pk_add_f32 v[40:41], v[68:69], v[40:41]
	s_waitcnt vmcnt(1)
	v_pk_add_f32 v[34:35], v[100:101], v[34:35]
	v_pk_add_f32 v[36:37], v[98:99], v[36:37]
	v_pk_mul_f32 v[70:71], v[150:151], v[38:39]
	v_pk_mul_f32 v[68:69], v[152:153], v[40:41]
	v_pk_mul_f32 v[98:99], v[154:155], v[34:35]
	v_pk_mul_f32 v[100:101], v[156:157], v[36:37]
	v_cvt_pk_bf16_f32 v68, v68, v69
	v_cvt_pk_bf16_f32 v69, v70, v71
	s_nop 0
	v_cvt_pk_bf16_f32 v70, v100, v101
	v_cvt_pk_bf16_f32 v71, v98, v99
	global_store_dwordx4 v[72:73], v[68:71], off
	global_load_dwordx4 v[68:71], v[186:187], off offset:512 nt
	s_nop 0
	global_load_dwordx4 v[98:101], v[186:187], off offset:528 nt
	v_lshl_add_u64 v[72:73], v[188:189], 0, v[148:149]
	v_lshlrev_b64 v[72:73], 1, v[72:73]
	v_cvt_pk_bf16_f32 v22, v22, v23
	v_cvt_pk_bf16_f32 v23, v24, v25
	v_cvt_pk_bf16_f32 v24, v18, v19
	v_cvt_pk_bf16_f32 v25, v20, v21
	v_lshl_add_u64 v[18:19], s[90:91], 0, v[72:73]
	global_store_dwordx4 v[18:19], v[22:25], off
	v_lshlrev_b32_e32 v20, 16, v24
	v_and_b32_e32 v21, 0xffff0000, v24
	v_lshlrev_b32_e32 v18, 16, v25
	v_and_b32_e32 v19, 0xffff0000, v25
	v_lshlrev_b32_e32 v24, 16, v22
	v_and_b32_e32 v25, 0xffff0000, v22
	v_lshlrev_b32_e32 v22, 16, v23
	v_and_b32_e32 v23, 0xffff0000, v23
	v_lshl_add_u64 v[72:73], s[96:97], 0, v[72:73]
	s_waitcnt vmcnt(2)
	v_pk_add_f32 v[22:23], v[70:71], v[22:23]
	v_pk_add_f32 v[24:25], v[68:69], v[24:25]
	s_waitcnt vmcnt(1)
; __device__ __forceinline__ unsigned cvt_pk_bf16(float lo, float hi) { unsigned r; asm volatile("v_cvt_pk_bf16_f32 %0, %1, %2" : "=v"(r) : "v"(lo), "v"(hi)); return r; }
;     __device__ __forceinline__ void operator()(const f32x4 (&acc)[2][2][4][2], const Unit& u, int wr, int wc, int fr, int fq) const {
;     ...
;                 for (int m = 0; m < 4; ++m) { const size_t off = (size_t)(row0 + ai * HALF + m * 16) * 2048 + col0 + bj * HALF;
;                     f32x4 x0 = __builtin_nontemporal_load((const f32x4*)(base + off)), x1 = __builtin_nontemporal_load((const f32x4*)(base + off + 4));
;                     if constexpr (HAS_DIN) { const u32x4 dw = __builtin_nontemporal_load((const u32x4*)(dbuf + off));
;                         x0 += (f32x4){__builtin_bit_cast(float, dw.x << 16), __builtin_bit_cast(float, dw.x & 0xffff0000u), __builtin_bit_cast(float, dw.y << 16), __builtin_bit_cast(float, dw.y & 0xffff0000u)};
;                         x1 += (f32x4){__builtin_bit_cast(float, dw.z << 16), __builtin_bit_cast(float, dw.z & 0xffff0000u), __builtin_bit_cast(float, dw.w << 16), __builtin_bit_cast(float, dw.w & 0xffff0000u)}; }
;                     f32x4 o0, o1;
;                     if constexpr (OUT_DELTA) { const f32x4 d0 = g0 * acc[ai][bj][m][0], d1 = g1 * acc[ai][bj][m][1];
;                         u32x4 w; w.x = cvt_pk_bf16(d0[0], d0[1]); w.y = cvt_pk_bf16(d0[2], d0[3]); w.z = cvt_pk_bf16(d1[0], d1[1]); w.w = cvt_pk_bf16(d1[2], d1[3]);
;                         *(u32x4*)(dbuf + off) = w;
;                         o0 = x0 + (f32x4){__builtin_bit_cast(float, w.x << 16), __builtin_bit_cast(float, w.x & 0xffff0000u), __builtin_bit_cast(float, w.y << 16), __builtin_bit_cast(float, w.y & 0xffff0000u)};
;                         o1 = x1 + (f32x4){__builtin_bit_cast(float, w.z << 16), __builtin_bit_cast(float, w.z & 0xffff0000u), __builtin_bit_cast(float, w.w << 16), __builtin_bit_cast(float, w.w & 0xffff0000u)}; }
;                     else { o0 = x0 + g0 * acc[ai][bj][m][0]; o1 = x1 + g1 * acc[ai][bj][m][1]; *(f32x4*)(out + off) = o0; *(f32x4*)(out + off + 4) = o1; }
;                     if (Hn) { const f32x4 h0 = o0 * G0, h1 = o1 * G1;
;                         u32x4 w; w.x = cvt_pk_bf16(h0[0], h0[1]); w.y = cvt_pk_bf16(h0[2], h0[3]); w.z = cvt_pk_bf16(h1[0], h1[1]); w.w = cvt_pk_bf16(h1[2], h1[3]);
;                         *(u32x4*)(Hn + off) = w;
	v_pk_add_f32 v[18:19], v[100:101], v[18:19]
	v_pk_add_f32 v[20:21], v[98:99], v[20:21]
	v_pk_mul_f32 v[70:71], v[150:151], v[22:23]
	v_pk_mul_f32 v[68:69], v[152:153], v[24:25]
	v_pk_mul_f32 v[98:99], v[154:155], v[18:19]
	v_pk_mul_f32 v[100:101], v[156:157], v[20:21]
	v_cvt_pk_bf16_f32 v68, v68, v69
	v_cvt_pk_bf16_f32 v69, v70, v71
	s_nop 0
	v_cvt_pk_bf16_f32 v70, v100, v101
	v_cvt_pk_bf16_f32 v71, v98, v99
	global_store_dwordx4 v[72:73], v[68:71], off
	global_load_dwordx4 v[68:71], v[190:191], off offset:512 nt
	s_nop 0
	global_load_dwordx4 v[98:101], v[190:191], off offset:528 nt
	v_lshl_add_u64 v[72:73], v[192:193], 0, v[148:149]
	v_lshlrev_b64 v[72:73], 1, v[72:73]
	v_cvt_pk_bf16_f32 v14, v14, v15
	v_cvt_pk_bf16_f32 v15, v16, v17
	v_cvt_pk_bf16_f32 v16, v10, v11
	v_cvt_pk_bf16_f32 v17, v12, v13
	v_lshl_add_u64 v[10:11], s[90:91], 0, v[72:73]
	global_store_dwordx4 v[10:11], v[14:17], off
	v_lshlrev_b32_e32 v12, 16, v16
	v_and_b32_e32 v13, 0xffff0000, v16
	v_lshlrev_b32_e32 v10, 16, v17
	v_and_b32_e32 v11, 0xffff0000, v17
	v_lshlrev_b32_e32 v16, 16, v14
	v_and_b32_e32 v17, 0xffff0000, v14
	v_lshlrev_b32_e32 v14, 16, v15
	v_and_b32_e32 v15, 0xffff0000, v15
	v_lshl_add_u64 v[72:73], s[96:97], 0, v[72:73]
	s_waitcnt vmcnt(2)
	v_pk_add_f32 v[14:15], v[70:71], v[14:15]
	v_pk_add_f32 v[16:17], v[68:69], v[16:17]
	s_waitcnt vmcnt(1)
	v_pk_add_f32 v[10:11], v[100:101], v[10:11]
	v_pk_add_f32 v[12:13], v[98:99], v[12:13]
	v_pk_mul_f32 v[70:71], v[150:151], v[14:15]
	v_pk_mul_f32 v[68:69], v[152:153], v[16:17]
	v_pk_mul_f32 v[98:99], v[154:155], v[10:11]
	v_pk_mul_f32 v[100:101], v[156:157], v[12:13]
	v_cvt_pk_bf16_f32 v68, v68, v69
	v_cvt_pk_bf16_f32 v69, v70, v71
	s_nop 0
	v_cvt_pk_bf16_f32 v70, v100, v101
	v_cvt_pk_bf16_f32 v71, v98, v99
	global_store_dwordx4 v[72:73], v[68:71], off
	global_load_dwordx4 v[68:71], v[194:195], off offset:512 nt
	s_nop 0
	global_load_dwordx4 v[98:101], v[194:195], off offset:528 nt
	v_lshl_add_u64 v[72:73], v[196:197], 0, v[148:149]
	v_lshlrev_b64 v[30:31], 1, v[72:73]
	v_cvt_pk_bf16_f32 v6, v6, v7
	v_cvt_pk_bf16_f32 v7, v8, v9
	v_cvt_pk_bf16_f32 v8, v2, v3
	v_cvt_pk_bf16_f32 v9, v4, v5
	v_lshl_add_u64 v[2:3], s[90:91], 0, v[30:31]
	global_store_dwordx4 v[2:3], v[6:9], off
	v_lshlrev_b32_e32 v4, 16, v8
	v_and_b32_e32 v5, 0xffff0000, v8
	v_lshlrev_b32_e32 v2, 16, v9
	v_and_b32_e32 v3, 0xffff0000, v9
	v_lshlrev_b32_e32 v8, 16, v6
	v_and_b32_e32 v9, 0xffff0000, v6
	v_lshlrev_b32_e32 v6, 16, v7
	v_and_b32_e32 v7, 0xffff0000, v7
	v_lshl_add_u64 v[30:31], s[96:97], 0, v[30:31]
	s_waitcnt vmcnt(2)
	v_pk_add_f32 v[8:9], v[68:69], v[8:9]
	v_pk_add_f32 v[6:7], v[70:71], v[6:7]
	v_pk_mul_f32 v[26:27], v[152:153], v[8:9]
	s_waitcnt vmcnt(1)
	v_pk_add_f32 v[2:3], v[100:101], v[2:3]
	v_pk_add_f32 v[4:5], v[98:99], v[4:5]
	v_pk_mul_f32 v[28:29], v[150:151], v[6:7]
	v_cvt_pk_bf16_f32 v26, v26, v27
	v_pk_mul_f32 v[32:33], v[154:155], v[2:3]
	v_cvt_pk_bf16_f32 v27, v28, v29
	v_pk_mul_f32 v[68:69], v[156:157], v[4:5]
	s_nop 0
	v_cvt_pk_bf16_f32 v28, v68, v69
	v_cvt_pk_bf16_f32 v29, v32, v33
	global_store_dwordx4 v[30:31], v[26:29], off
	s_nop 1
	v_and_b32_e32 v27, 64, v218
	v_xor_b32_e32 v26, 16, v218
	v_add_u32_e32 v27, 64, v27
	v_cmp_lt_i32_e32 vcc, v26, v27
	s_nop 1
	v_cndmask_b32_e32 v26, v218, v26, vcc
	v_lshlrev_b32_e32 v28, 2, v26
	v_xor_b32_e32 v26, 32, v218
	v_cmp_lt_i32_e32 vcc, v26, v27
	s_nop 1
	v_cndmask_b32_e32 v26, v218, v26, vcc
	v_lshlrev_b32_e32 v29, 2, v26
	ds_bpermute_b32 v26, v28, v66
	s_waitcnt lgkmcnt(0)
	v_add_f32_e32 v30, v66, v26
	ds_bpermute_b32 v31, v29, v30
	v_lshl_add_u64 v[26:27], v[146:147], 3, s[42:43]
	s_and_saveexec_b64 s[4:5], s[0:1]
	s_mov_b32 s8, 0x2f800000
	s_mov_b32 s9, 0xcf800000
	s_cbranch_execz .LBB0_558
	s_waitcnt lgkmcnt(0)
	v_add_f32_e32 v30, v30, v31
	v_mul_f32_e32 v30, 0x47800000, v30
	v_rndne_f32_e32 v30, v30
	v_mul_f32_e64 v31, |v30|, s8
	v_floor_f32_e32 v31, v31
	v_fma_f32 v32, v31, s9, |v30|
	v_cvt_u32_f32_e32 v32, v32
	v_cvt_u32_f32_e32 v31, v31
	v_ashrrev_i32_e32 v33, 31, v30
	v_xor_b32_e32 v30, v32, v33
	v_xor_b32_e32 v31, v31, v33
	v_sub_co_u32_e32 v30, vcc, v30, v33
	s_nop 1
	v_subb_co_u32_e32 v31, vcc, v31, v33, vcc
	global_atomic_add_x2 v[26:27], v[30:31], off

; #define PG8_STAGE(bufoff, gbase, voff) do { const char* gb_ = (const char*)(gbase); asm volatile("" : "+s"(gb_)); _Pragma("unroll") for (int _i = 0; _i < 2; ++_i) { unsigned vo_ = (voff)[_i]; asm volatile("" : "+v"(vo_));        \
;         __builtin_amdgcn_global_load_lds((const unsigned*)(gb_ + vo_), (PG8_LAS unsigned*)(lds + (bufoff) + ldsw + _i * 8192), 16, 0, 0); } } while (0)
; #define PG8_LDA(dst, b, h) do { _Pragma("unroll") for (int m = 0; m < 4; ++m) _Pragma("unroll") for (int k = 0; k < 2; ++k) dst[m][k] = *(const PG8_LAS bf16x8*)(lds + PG8_SA(b, h) + aoff + m * 2048 + k * 1024); } while (0)
; #define PG8_LDB(dst, b, h) do { _Pragma("unroll") for (int n = 0; n < 2; ++n) _Pragma("unroll") for (int k = 0; k < 2; ++k) dst[n][k] = *(const PG8_LAS bf16x8*)(lds + PG8_SB(b, h) + boff + n * 2048 + k * 1024); } while (0)
; #define PG8_MMA(ai, bj, At, Bt) do { __builtin_amdgcn_s_setprio(1); _Pragma("unroll") for (int m = 0; m < 4; ++m) _Pragma("unroll") for (int n = 0; n < 2; ++n) _Pragma("unroll") for (int k = 0; k < 2; ++k) \
;         acc[ai][bj][m][n] = __builtin_amdgcn_mfma_f32_16x16x32_bf16(Bt[n][k], At[m][k], acc[ai][bj][m][n], 0, 0, 0); __builtin_amdgcn_s_setprio(0); } while (0)
; #define PG8_WAIT_V(n) asm volatile("s_waitcnt vmcnt(" #n ")" ::: "memory")
; template <class Epi, class Sched, bool ALIGN_EPI = false, bool SP2 = false>
; __device__ __forceinline__ void gemm_phase(PG8_LAS unsigned char* lds, const Gemm g, const Sched& S, const Epi& E) {
;     ...
;             const bool last = (t == nt - 2);
;             const char* a1 = cA + (size_t)(t + 1) * kstep;
;             const char* a2 = last ? nA : cA + (size_t)(t + 2) * kstep; const char* b2 = last ? nB : cB + (size_t)(t + 2) * kstep;
;             const char* a3 = a2 + kstep; const char* b3 = b2 + kstep;
;             if (last && has_next) S.a_ready(nxt);
;             if constexpr (SP2) {
;             PG8_LDB(B0, 0, 0); PG8_LDB(B1, 0, 1); PG8_SCHED; PG8_LDA(At, 0, 0); PG8_STAGE(PG8_SA(1, 1), a1 + hstep, voffA);
;             PG8_WAIT_V(8); PG8_WAIT_L(0); PG8_BAR; PG8_MMA(0, 0, At, B0); PG8_MMA(0, 1, At, B1); PG8_BAR; PG8_SCHED;
;             PG8_LDA(At, 0, 1); PG8_STAGE(PG8_SB(0, 0), b2, voffB); PG8_STAGE(PG8_SB(0, 1), b2 + hstep, voffB); PG8_STAGE(PG8_SA(0, 0), a2, voffA);
;             PG8_WAIT_V(8); PG8_WAIT_L(0); PG8_BAR; PG8_MMA(1, 0, At, B0); PG8_MMA(1, 1, At, B1); PG8_BAR; PG8_SCHED;
.LBB0_634:
	s_add_u32 s16, s14, 0x100
	s_addc_u32 s17, s15, 0
	s_cmp_eq_u32 s53, 28
	s_cselect_b32 s22, s49, s16
	s_cselect_b32 s23, s7, s17
	s_cselect_b32 s20, s50, s51
	s_cselect_b32 s21, s5, s52
	s_add_u32 s18, s22, 0x80
	s_addc_u32 s19, s23, 0
	s_add_i32 s54, 0, 0x10000
	s_add_i32 s55, 0, 0x14000
	ds_read_b128 v[82:85], v244
	ds_read_b128 v[86:89], v244 offset:1024
	ds_read_b128 v[90:93], v244 offset:2048
	ds_read_b128 v[94:97], v244 offset:3072
	ds_read_b128 v[146:149], v244 offset:16384
	ds_read_b128 v[150:153], v244 offset:17408
	ds_read_b128 v[154:157], v244 offset:18432
	ds_read_b128 v[158:161], v244 offset:19456
	s_add_u32 s14, s14, 0x80080
	s_addc_u32 s15, s15, 0
	ds_read_b128 v[178:181], v188
	ds_read_b128 v[190:193], v188 offset:1024
	ds_read_b128 v[194:197], v188 offset:2048
	ds_read_b128 v[198:201], v188 offset:3072
	ds_read_b128 v[202:205], v188 offset:4096
	ds_read_b128 v[206:209], v188 offset:5120
	ds_read_b128 v[210:213], v188 offset:6144
	ds_read_b128 v[220:223], v188 offset:7168
	s_add_i32 m0, s27, 0xc000
	s_nop 0
	global_load_lds_dwordx4 v1, s[14:15] sc0
	s_add_i32 m0, s27, 0xe000
	s_nop 0
	global_load_lds_dwordx4 v164, s[14:15] sc0
	s_waitcnt vmcnt(8)
	s_waitcnt lgkmcnt(0)
	s_barrier
	s_setprio 1
	s_waitcnt lgkmcnt(0)
	v_mfma_f32_16x16x32_bf16 v[142:145], v[82:85], v[178:181], v[142:145]
	v_mfma_f32_16x16x32_bf16 v[142:145], v[86:89], v[190:193], v[142:145]
	v_mfma_f32_16x16x32_bf16 v[126:129], v[82:85], v[194:197], v[126:129]
	v_mfma_f32_16x16x32_bf16 v[126:129], v[86:89], v[198:201], v[126:129]
	v_mfma_f32_16x16x32_bf16 v[110:113], v[82:85], v[202:205], v[110:113]
	v_mfma_f32_16x16x32_bf16 v[110:113], v[86:89], v[206:209], v[110:113]
	v_mfma_f32_16x16x32_bf16 v[78:81], v[82:85], v[210:213], v[78:81]
	v_mfma_f32_16x16x32_bf16 v[78:81], v[86:89], v[220:223], v[78:81]
	v_mfma_f32_16x16x32_bf16 v[138:141], v[90:93], v[178:181], v[138:141]
	v_mfma_f32_16x16x32_bf16 v[138:141], v[94:97], v[190:193], v[138:141]
	v_mfma_f32_16x16x32_bf16 v[122:125], v[90:93], v[194:197], v[122:125]
	v_mfma_f32_16x16x32_bf16 v[122:125], v[94:97], v[198:201], v[122:125]
	v_mfma_f32_16x16x32_bf16 v[106:109], v[90:93], v[202:205], v[106:109]
	v_mfma_f32_16x16x32_bf16 v[106:109], v[94:97], v[206:209], v[106:109]
	v_mfma_f32_16x16x32_bf16 v[74:77], v[90:93], v[210:213], v[74:77]
	v_mfma_f32_16x16x32_bf16 v[74:77], v[94:97], v[220:223], v[74:77]
	s_setprio 0
	s_setprio 1
	v_mfma_f32_16x16x32_bf16 v[134:137], v[146:149], v[178:181], v[134:137]
	v_mfma_f32_16x16x32_bf16 v[134:137], v[150:153], v[190:193], v[134:137]
	v_mfma_f32_16x16x32_bf16 v[118:121], v[146:149], v[194:197], v[118:121]
	v_mfma_f32_16x16x32_bf16 v[118:121], v[150:153], v[198:201], v[118:121]
	v_mfma_f32_16x16x32_bf16 v[102:105], v[146:149], v[202:205], v[102:105]
	v_mfma_f32_16x16x32_bf16 v[102:105], v[150:153], v[206:209], v[102:105]
	v_mfma_f32_16x16x32_bf16 v[70:73], v[146:149], v[210:213], v[70:73]
	v_mfma_f32_16x16x32_bf16 v[70:73], v[150:153], v[220:223], v[70:73]
	v_mfma_f32_16x16x32_bf16 v[130:133], v[154:157], v[178:181], v[130:133]
	v_mfma_f32_16x16x32_bf16 v[130:133], v[158:161], v[190:193], v[130:133]
	v_mfma_f32_16x16x32_bf16 v[114:117], v[154:157], v[194:197], v[114:117]
	v_mfma_f32_16x16x32_bf16 v[114:117], v[158:161], v[198:201], v[114:117]
	v_mfma_f32_16x16x32_bf16 v[98:101], v[154:157], v[202:205], v[98:101]
	v_mfma_f32_16x16x32_bf16 v[98:101], v[158:161], v[206:209], v[98:101]
	v_mfma_f32_16x16x32_bf16 v[66:69], v[154:157], v[210:213], v[66:69]
	v_mfma_f32_16x16x32_bf16 v[66:69], v[158:161], v[220:223], v[66:69]
	s_setprio 0
	s_barrier
	s_mov_b64 s[14:15], s[20:21]
	s_add_i32 s54, s54, s26
	ds_read_b128 v[178:181], v188 offset:16384
	ds_read_b128 v[190:193], v188 offset:17408
	ds_read_b128 v[194:197], v188 offset:18432
	ds_read_b128 v[198:201], v188 offset:19456
	ds_read_b128 v[202:205], v188 offset:20480
	ds_read_b128 v[206:209], v188 offset:21504
	ds_read_b128 v[210:213], v188 offset:22528
	ds_read_b128 v[220:223], v188 offset:23552
	s_mov_b32 m0, s54
	s_nop 0
	global_load_lds_dwordx4 v162, s[14:15] sc0
	s_add_i32 m0, s54, 0x2000
	s_nop 0
	global_load_lds_dwordx4 v184, s[14:15] sc0
	s_add_u32 s14, s20, 0x80000
	s_addc_u32 s15, s21, 0
	s_add_i32 s54, s55, s26
	s_mov_b32 m0, s54
	s_nop 0
	global_load_lds_dwordx4 v162, s[14:15] sc0
	s_add_i32 m0, s54, 0x2000
	s_nop 0
	global_load_lds_dwordx4 v184, s[14:15] sc0
	s_mov_b64 s[14:15], s[22:23]
	s_mov_b32 m0, s27
	s_nop 0
	global_load_lds_dwordx4 v1, s[14:15] sc0
	s_mov_b32 m0, s28
	s_nop 0
	global_load_lds_dwordx4 v164, s[14:15] sc0
	s_waitcnt vmcnt(8)
	s_waitcnt lgkmcnt(0)
	s_barrier
; #define PG8_STAGE(bufoff, gbase, voff) do { const char* gb_ = (const char*)(gbase); asm volatile("" : "+s"(gb_)); _Pragma("unroll") for (int _i = 0; _i < 2; ++_i) { unsigned vo_ = (voff)[_i]; asm volatile("" : "+v"(vo_));        \
;         __builtin_amdgcn_global_load_lds((const unsigned*)(gb_ + vo_), (PG8_LAS unsigned*)(lds + (bufoff) + ldsw + _i * 8192), 16, 0, 0); } } while (0)
; #define PG8_LDA(dst, b, h) do { _Pragma("unroll") for (int m = 0; m < 4; ++m) _Pragma("unroll") for (int k = 0; k < 2; ++k) dst[m][k] = *(const PG8_LAS bf16x8*)(lds + PG8_SA(b, h) + aoff + m * 2048 + k * 1024); } while (0)
; #define PG8_LDB(dst, b, h) do { _Pragma("unroll") for (int n = 0; n < 2; ++n) _Pragma("unroll") for (int k = 0; k < 2; ++k) dst[n][k] = *(const PG8_LAS bf16x8*)(lds + PG8_SB(b, h) + boff + n * 2048 + k * 1024); } while (0)
; #define PG8_MMA(ai, bj, At, Bt) do { __builtin_amdgcn_s_setprio(1); _Pragma("unroll") for (int m = 0; m < 4; ++m) _Pragma("unroll") for (int n = 0; n < 2; ++n) _Pragma("unroll") for (int k = 0; k < 2; ++k) \
;         acc[ai][bj][m][n] = __builtin_amdgcn_mfma_f32_16x16x32_bf16(Bt[n][k], At[m][k], acc[ai][bj][m][n], 0, 0, 0); __builtin_amdgcn_s_setprio(0); } while (0)
; #define PG8_WAIT_V(n) asm volatile("s_waitcnt vmcnt(" #n ")" ::: "memory")
; #define PG8_WAIT_L(n) asm volatile("s_waitcnt lgkmcnt(" #n ")" ::: "memory")
; #define PG8_BAR __builtin_amdgcn_s_barrier()
; #define PG8_SCHED __builtin_amdgcn_sched_barrier(0)
; template <class Epi, class Sched, bool ALIGN_EPI = false, bool SP2 = false>
; __device__ __forceinline__ void gemm_phase(PG8_LAS unsigned char* lds, const Gemm g, const Sched& S, const Epi& E) {
;     ...
;             PG8_WAIT_V(8); PG8_WAIT_L(0); PG8_BAR; PG8_MMA(1, 0, At, B0); PG8_MMA(1, 1, At, B1); PG8_BAR; PG8_SCHED;
;             PG8_LDB(B0, 1, 0); PG8_LDB(B1, 1, 1); PG8_SCHED; PG8_LDA(At, 1, 0); PG8_STAGE(PG8_SA(0, 1), a2 + hstep, voffA);
;             PG8_WAIT_V(8); PG8_WAIT_L(0); PG8_BAR; PG8_MMA(0, 0, At, B0); PG8_MMA(0, 1, At, B1); PG8_BAR; PG8_SCHED;
	s_setprio 1
	s_waitcnt lgkmcnt(0)
	v_mfma_f32_16x16x32_bf16 v[62:65], v[82:85], v[178:181], v[62:65]
	v_mfma_f32_16x16x32_bf16 v[62:65], v[86:89], v[190:193], v[62:65]
	v_mfma_f32_16x16x32_bf16 v[46:49], v[82:85], v[194:197], v[46:49]
	v_mfma_f32_16x16x32_bf16 v[46:49], v[86:89], v[198:201], v[46:49]
	v_mfma_f32_16x16x32_bf16 v[30:33], v[82:85], v[202:205], v[30:33]
	v_mfma_f32_16x16x32_bf16 v[30:33], v[86:89], v[206:209], v[30:33]
	v_mfma_f32_16x16x32_bf16 v[14:17], v[82:85], v[210:213], v[14:17]
	v_mfma_f32_16x16x32_bf16 v[14:17], v[86:89], v[220:223], v[14:17]
	v_mfma_f32_16x16x32_bf16 v[58:61], v[90:93], v[178:181], v[58:61]
	v_mfma_f32_16x16x32_bf16 v[58:61], v[94:97], v[190:193], v[58:61]
	v_mfma_f32_16x16x32_bf16 v[42:45], v[90:93], v[194:197], v[42:45]
	v_mfma_f32_16x16x32_bf16 v[42:45], v[94:97], v[198:201], v[42:45]
	v_mfma_f32_16x16x32_bf16 v[26:29], v[90:93], v[202:205], v[26:29]
	v_mfma_f32_16x16x32_bf16 v[26:29], v[94:97], v[206:209], v[26:29]
	v_mfma_f32_16x16x32_bf16 v[10:13], v[90:93], v[210:213], v[10:13]
	v_mfma_f32_16x16x32_bf16 v[10:13], v[94:97], v[220:223], v[10:13]
	s_setprio 0
	s_setprio 1
	v_mfma_f32_16x16x32_bf16 v[54:57], v[146:149], v[178:181], v[54:57]
	v_mfma_f32_16x16x32_bf16 v[54:57], v[150:153], v[190:193], v[54:57]
	v_mfma_f32_16x16x32_bf16 v[38:41], v[146:149], v[194:197], v[38:41]
	v_mfma_f32_16x16x32_bf16 v[38:41], v[150:153], v[198:201], v[38:41]
	v_mfma_f32_16x16x32_bf16 v[22:25], v[146:149], v[202:205], v[22:25]
	v_mfma_f32_16x16x32_bf16 v[22:25], v[150:153], v[206:209], v[22:25]
	v_mfma_f32_16x16x32_bf16 v[6:9], v[146:149], v[210:213], v[6:9]
	v_mfma_f32_16x16x32_bf16 v[6:9], v[150:153], v[220:223], v[6:9]
	v_mfma_f32_16x16x32_bf16 v[50:53], v[154:157], v[178:181], v[50:53]
	v_mfma_f32_16x16x32_bf16 v[50:53], v[158:161], v[190:193], v[50:53]
	v_mfma_f32_16x16x32_bf16 v[34:37], v[154:157], v[194:197], v[34:37]
	v_mfma_f32_16x16x32_bf16 v[34:37], v[158:161], v[198:201], v[34:37]
	v_mfma_f32_16x16x32_bf16 v[18:21], v[154:157], v[202:205], v[18:21]
	v_mfma_f32_16x16x32_bf16 v[18:21], v[158:161], v[206:209], v[18:21]
	v_mfma_f32_16x16x32_bf16 v[2:5], v[154:157], v[210:213], v[2:5]
	v_mfma_f32_16x16x32_bf16 v[2:5], v[158:161], v[220:223], v[2:5]
	s_setprio 0
	s_barrier
	s_add_i32 s54, 0, 0x18000
	s_add_i32 s55, 0, 0x1c000
	ds_read_b128 v[82:85], v244 offset:32768
	ds_read_b128 v[86:89], v244 offset:33792
	ds_read_b128 v[90:93], v244 offset:34816
	ds_read_b128 v[94:97], v244 offset:35840
	ds_read_b128 v[146:149], v244 offset:49152
	ds_read_b128 v[150:153], v244 offset:50176
	ds_read_b128 v[154:157], v244 offset:51200
	ds_read_b128 v[158:161], v244 offset:52224
	s_add_u32 s14, s22, 0x80000
	s_addc_u32 s15, s23, 0
	s_mov_b32 m0, s29
	ds_read_b128 v[178:181], v188 offset:32768
	ds_read_b128 v[190:193], v188 offset:33792
	ds_read_b128 v[194:197], v188 offset:34816
	ds_read_b128 v[198:201], v188 offset:35840
	ds_read_b128 v[202:205], v188 offset:36864
	ds_read_b128 v[206:209], v188 offset:37888
	ds_read_b128 v[210:213], v188 offset:38912
	ds_read_b128 v[220:223], v188 offset:39936
	s_nop 0
	global_load_lds_dwordx4 v1, s[14:15] sc0
	s_mov_b32 m0, s33
	s_nop 0
	global_load_lds_dwordx4 v164, s[14:15] sc0
	s_waitcnt vmcnt(8)
	s_waitcnt lgkmcnt(0)
	s_barrier
	s_setprio 1
	s_waitcnt lgkmcnt(0)
	v_mfma_f32_16x16x32_bf16 v[142:145], v[82:85], v[178:181], v[142:145]
	v_mfma_f32_16x16x32_bf16 v[142:145], v[86:89], v[190:193], v[142:145]
	v_mfma_f32_16x16x32_bf16 v[126:129], v[82:85], v[194:197], v[126:129]
	v_mfma_f32_16x16x32_bf16 v[126:129], v[86:89], v[198:201], v[126:129]
	v_mfma_f32_16x16x32_bf16 v[110:113], v[82:85], v[202:205], v[110:113]
	v_mfma_f32_16x16x32_bf16 v[110:113], v[86:89], v[206:209], v[110:113]
	v_mfma_f32_16x16x32_bf16 v[78:81], v[82:85], v[210:213], v[78:81]
	v_mfma_f32_16x16x32_bf16 v[78:81], v[86:89], v[220:223], v[78:81]
	v_mfma_f32_16x16x32_bf16 v[138:141], v[90:93], v[178:181], v[138:141]
	v_mfma_f32_16x16x32_bf16 v[138:141], v[94:97], v[190:193], v[138:141]
	v_mfma_f32_16x16x32_bf16 v[122:125], v[90:93], v[194:197], v[122:125]
	v_mfma_f32_16x16x32_bf16 v[122:125], v[94:97], v[198:201], v[122:125]
	v_mfma_f32_16x16x32_bf16 v[106:109], v[90:93], v[202:205], v[106:109]
	v_mfma_f32_16x16x32_bf16 v[106:109], v[94:97], v[206:209], v[106:109]
	v_mfma_f32_16x16x32_bf16 v[74:77], v[90:93], v[210:213], v[74:77]
	v_mfma_f32_16x16x32_bf16 v[74:77], v[94:97], v[220:223], v[74:77]
	s_setprio 0
	s_setprio 1
	v_mfma_f32_16x16x32_bf16 v[134:137], v[146:149], v[178:181], v[134:137]
	v_mfma_f32_16x16x32_bf16 v[134:137], v[150:153], v[190:193], v[134:137]
	v_mfma_f32_16x16x32_bf16 v[118:121], v[146:149], v[194:197], v[118:121]
	v_mfma_f32_16x16x32_bf16 v[118:121], v[150:153], v[198:201], v[118:121]
	v_mfma_f32_16x16x32_bf16 v[102:105], v[146:149], v[202:205], v[102:105]
	v_mfma_f32_16x16x32_bf16 v[102:105], v[150:153], v[206:209], v[102:105]
	v_mfma_f32_16x16x32_bf16 v[70:73], v[146:149], v[210:213], v[70:73]
	v_mfma_f32_16x16x32_bf16 v[70:73], v[150:153], v[220:223], v[70:73]
	v_mfma_f32_16x16x32_bf16 v[130:133], v[154:157], v[178:181], v[130:133]
	v_mfma_f32_16x16x32_bf16 v[130:133], v[158:161], v[190:193], v[130:133]
	v_mfma_f32_16x16x32_bf16 v[114:117], v[154:157], v[194:197], v[114:117]
	v_mfma_f32_16x16x32_bf16 v[114:117], v[158:161], v[198:201], v[114:117]
	v_mfma_f32_16x16x32_bf16 v[98:101], v[154:157], v[202:205], v[98:101]
	v_mfma_f32_16x16x32_bf16 v[98:101], v[158:161], v[206:209], v[98:101]
	v_mfma_f32_16x16x32_bf16 v[66:69], v[154:157], v[210:213], v[66:69]
	v_mfma_f32_16x16x32_bf16 v[66:69], v[158:161], v[220:223], v[66:69]
	s_setprio 0
	s_barrier
; #define PG8_STAGE(bufoff, gbase, voff) do { const char* gb_ = (const char*)(gbase); asm volatile("" : "+s"(gb_)); _Pragma("unroll") for (int _i = 0; _i < 2; ++_i) { unsigned vo_ = (voff)[_i]; asm volatile("" : "+v"(vo_));        \
;         __builtin_amdgcn_global_load_lds((const unsigned*)(gb_ + vo_), (PG8_LAS unsigned*)(lds + (bufoff) + ldsw + _i * 8192), 16, 0, 0); } } while (0)
; #define PG8_LDA(dst, b, h) do { _Pragma("unroll") for (int m = 0; m < 4; ++m) _Pragma("unroll") for (int k = 0; k < 2; ++k) dst[m][k] = *(const PG8_LAS bf16x8*)(lds + PG8_SA(b, h) + aoff + m * 2048 + k * 1024); } while (0)
; #define PG8_MMA(ai, bj, At, Bt) do { __builtin_amdgcn_s_setprio(1); _Pragma("unroll") for (int m = 0; m < 4; ++m) _Pragma("unroll") for (int n = 0; n < 2; ++n) _Pragma("unroll") for (int k = 0; k < 2; ++k) \
;         acc[ai][bj][m][n] = __builtin_amdgcn_mfma_f32_16x16x32_bf16(Bt[n][k], At[m][k], acc[ai][bj][m][n], 0, 0, 0); __builtin_amdgcn_s_setprio(0); } while (0)
; #define PG8_WAIT_V(n) asm volatile("s_waitcnt vmcnt(" #n ")" ::: "memory")
; #define PG8_WAIT_L(n) asm volatile("s_waitcnt lgkmcnt(" #n ")" ::: "memory")
; #define PG8_BAR __builtin_amdgcn_s_barrier()
; #define PG8_SCHED __builtin_amdgcn_sched_barrier(0)
; template <class Epi, class Sched, bool ALIGN_EPI = false, bool SP2 = false>
; __device__ __forceinline__ void gemm_phase(PG8_LAS unsigned char* lds, const Gemm g, const Sched& S, const Epi& E) {
;     ...
;             PG8_LDA(At, 1, 1); PG8_STAGE(PG8_SB(1, 0), b3, voffB); PG8_STAGE(PG8_SB(1, 1), b3 + hstep, voffB); PG8_STAGE(PG8_SA(1, 0), a3, voffA);
;             PG8_WAIT_V(8); PG8_WAIT_L(0); PG8_BAR; PG8_MMA(1, 0, At, B0); PG8_MMA(1, 1, At, B1); PG8_BAR; PG8_SCHED;
;     ...
;         if constexpr (ALIGN_EPI) { if (wr == 0) PG8_BAR; }
	s_add_u32 s14, s20, 0x80
	s_addc_u32 s15, s21, 0
	s_add_i32 s22, s54, s26
	ds_read_b128 v[178:181], v188 offset:49152
	ds_read_b128 v[190:193], v188 offset:50176
	ds_read_b128 v[194:197], v188 offset:51200
	ds_read_b128 v[198:201], v188 offset:52224
	ds_read_b128 v[202:205], v188 offset:53248
	ds_read_b128 v[206:209], v188 offset:54272
	ds_read_b128 v[210:213], v188 offset:55296
	ds_read_b128 v[220:223], v188 offset:56320
	s_mov_b32 m0, s22
	s_nop 0
	global_load_lds_dwordx4 v162, s[14:15] sc0
	s_add_i32 m0, s22, 0x2000
	s_nop 0
	global_load_lds_dwordx4 v184, s[14:15] sc0
	s_add_u32 s14, s20, 0x80080
	s_addc_u32 s15, s21, 0
	s_add_i32 s20, s55, s26
	s_mov_b32 m0, s20
	s_nop 0
	global_load_lds_dwordx4 v162, s[14:15] sc0
	s_add_i32 m0, s20, 0x2000
	s_nop 0
	global_load_lds_dwordx4 v184, s[14:15] sc0
	s_mov_b32 m0, s38
	s_nop 0
	global_load_lds_dwordx4 v1, s[18:19] sc0
	s_mov_b32 m0, s39
	s_nop 0
	global_load_lds_dwordx4 v164, s[18:19] sc0
	s_waitcnt vmcnt(8)
	s_waitcnt lgkmcnt(0)
	s_barrier
	s_setprio 1
	s_waitcnt lgkmcnt(0)
	v_mfma_f32_16x16x32_bf16 v[62:65], v[82:85], v[178:181], v[62:65]
	v_mfma_f32_16x16x32_bf16 v[62:65], v[86:89], v[190:193], v[62:65]
	v_mfma_f32_16x16x32_bf16 v[46:49], v[82:85], v[194:197], v[46:49]
	v_mfma_f32_16x16x32_bf16 v[46:49], v[86:89], v[198:201], v[46:49]
	v_mfma_f32_16x16x32_bf16 v[30:33], v[82:85], v[202:205], v[30:33]
	v_mfma_f32_16x16x32_bf16 v[30:33], v[86:89], v[206:209], v[30:33]
	v_mfma_f32_16x16x32_bf16 v[14:17], v[82:85], v[210:213], v[14:17]
	v_mfma_f32_16x16x32_bf16 v[14:17], v[86:89], v[220:223], v[14:17]
	v_mfma_f32_16x16x32_bf16 v[58:61], v[90:93], v[178:181], v[58:61]
	v_mfma_f32_16x16x32_bf16 v[58:61], v[94:97], v[190:193], v[58:61]
	v_mfma_f32_16x16x32_bf16 v[42:45], v[90:93], v[194:197], v[42:45]
	v_mfma_f32_16x16x32_bf16 v[42:45], v[94:97], v[198:201], v[42:45]
	v_mfma_f32_16x16x32_bf16 v[26:29], v[90:93], v[202:205], v[26:29]
	v_mfma_f32_16x16x32_bf16 v[26:29], v[94:97], v[206:209], v[26:29]
	v_mfma_f32_16x16x32_bf16 v[10:13], v[90:93], v[210:213], v[10:13]
	v_mfma_f32_16x16x32_bf16 v[10:13], v[94:97], v[220:223], v[10:13]
	s_setprio 0
	s_setprio 1
	v_mfma_f32_16x16x32_bf16 v[54:57], v[146:149], v[178:181], v[54:57]
	v_mfma_f32_16x16x32_bf16 v[54:57], v[150:153], v[190:193], v[54:57]
	v_mfma_f32_16x16x32_bf16 v[38:41], v[146:149], v[194:197], v[38:41]
	v_mfma_f32_16x16x32_bf16 v[38:41], v[150:153], v[198:201], v[38:41]
	v_mfma_f32_16x16x32_bf16 v[22:25], v[146:149], v[202:205], v[22:25]
	v_mfma_f32_16x16x32_bf16 v[22:25], v[150:153], v[206:209], v[22:25]
	v_mfma_f32_16x16x32_bf16 v[6:9], v[146:149], v[210:213], v[6:9]
	v_mfma_f32_16x16x32_bf16 v[6:9], v[150:153], v[220:223], v[6:9]
	v_mfma_f32_16x16x32_bf16 v[50:53], v[154:157], v[178:181], v[50:53]
	v_mfma_f32_16x16x32_bf16 v[50:53], v[158:161], v[190:193], v[50:53]
	v_mfma_f32_16x16x32_bf16 v[34:37], v[154:157], v[194:197], v[34:37]
	v_mfma_f32_16x16x32_bf16 v[34:37], v[158:161], v[198:201], v[34:37]
	v_mfma_f32_16x16x32_bf16 v[18:21], v[154:157], v[202:205], v[18:21]
	v_mfma_f32_16x16x32_bf16 v[18:21], v[158:161], v[206:209], v[18:21]
	v_mfma_f32_16x16x32_bf16 v[2:5], v[154:157], v[210:213], v[2:5]
	v_mfma_f32_16x16x32_bf16 v[2:5], v[158:161], v[220:223], v[2:5]
	s_setprio 0
	s_barrier
	s_add_i32 s53, s53, 2
	s_add_u32 s51, s51, 0x100
	s_addc_u32 s52, s52, 0
	s_cmp_gt_u32 s53, 29
	s_mov_b64 s[14:15], s[16:17]
	s_cbranch_scc0 .LBB0_634
	s_and_b64 vcc, exec, s[2:3]
	s_cbranch_vccz .LBB0_637
	s_barrier

; #define PG8_STAGE(bufoff, gbase, voff) do { const char* gb_ = (const char*)(gbase); asm volatile("" : "+s"(gb_)); _Pragma("unroll") for (int _i = 0; _i < 2; ++_i) { unsigned vo_ = (voff)[_i]; asm volatile("" : "+v"(vo_));        \
;         __builtin_amdgcn_global_load_lds((const unsigned*)(gb_ + vo_), (PG8_LAS unsigned*)(lds + (bufoff) + ldsw + _i * 8192), 16, 0, 0); } } while (0)
; #define PG8_LDA(dst, b, h) do { _Pragma("unroll") for (int m = 0; m < 4; ++m) _Pragma("unroll") for (int k = 0; k < 2; ++k) dst[m][k] = *(const PG8_LAS bf16x8*)(lds + PG8_SA(b, h) + aoff + m * 2048 + k * 1024); } while (0)
; #define PG8_LDB(dst, b, h) do { _Pragma("unroll") for (int n = 0; n < 2; ++n) _Pragma("unroll") for (int k = 0; k < 2; ++k) dst[n][k] = *(const PG8_LAS bf16x8*)(lds + PG8_SB(b, h) + boff + n * 2048 + k * 1024); } while (0)
; #define PG8_MMA(ai, bj, At, Bt) do { __builtin_amdgcn_s_setprio(1); _Pragma("unroll") for (int m = 0; m < 4; ++m) _Pragma("unroll") for (int n = 0; n < 2; ++n) _Pragma("unroll") for (int k = 0; k < 2; ++k) \
;         acc[ai][bj][m][n] = __builtin_amdgcn_mfma_f32_16x16x32_bf16(Bt[n][k], At[m][k], acc[ai][bj][m][n], 0, 0, 0); __builtin_amdgcn_s_setprio(0); } while (0)
; #define PG8_WAIT_V(n) asm volatile("s_waitcnt vmcnt(" #n ")" ::: "memory")
; template <class Epi, class Sched, bool ALIGN_EPI = false, bool SP2 = false>
; __device__ __forceinline__ void gemm_phase(PG8_LAS unsigned char* lds, const Gemm g, const Sched& S, const Epi& E) {
;     ...
;             const bool last = (t == nt - 2);
;             const char* a1 = cA + (size_t)(t + 1) * kstep;
;             const char* a2 = last ? nA : cA + (size_t)(t + 2) * kstep; const char* b2 = last ? nB : cB + (size_t)(t + 2) * kstep;
;             const char* a3 = a2 + kstep; const char* b3 = b2 + kstep;
;             if (last && has_next) S.a_ready(nxt);
;             if constexpr (SP2) {
;             PG8_LDB(B0, 0, 0); PG8_LDB(B1, 0, 1); PG8_SCHED; PG8_LDA(At, 0, 0); PG8_STAGE(PG8_SA(1, 1), a1 + hstep, voffA);
;             PG8_WAIT_V(8); PG8_WAIT_L(0); PG8_BAR; PG8_MMA(0, 0, At, B0); PG8_MMA(0, 1, At, B1); PG8_BAR; PG8_SCHED;
;             PG8_LDA(At, 0, 1); PG8_STAGE(PG8_SB(0, 0), b2, voffB); PG8_STAGE(PG8_SB(0, 1), b2 + hstep, voffB); PG8_STAGE(PG8_SA(0, 0), a2, voffA);
;             PG8_WAIT_V(8); PG8_WAIT_L(0); PG8_BAR; PG8_MMA(1, 0, At, B0); PG8_MMA(1, 1, At, B1); PG8_BAR; PG8_SCHED;
.LBB0_707:
	s_add_u32 s2, s4, 0x100
	s_addc_u32 s3, s5, 0
	s_cmpk_eq_i32 s35, 0x54
	s_cselect_b32 s10, s52, s2
	s_cselect_b32 s11, s53, s3
	s_cselect_b32 s8, s42, s31
	s_cselect_b32 s9, s43, s34
	s_add_u32 s6, s10, 0x80
	s_addc_u32 s7, s11, 0
	s_add_i32 s38, 0, 0x10000
	s_add_i32 s39, 0, 0x14000
	ds_read_b128 v[34:37], v244
	ds_read_b128 v[38:41], v244 offset:1024
	ds_read_b128 v[98:101], v244 offset:2048
	ds_read_b128 v[102:105], v244 offset:3072
	ds_read_b128 v[146:149], v244 offset:16384
	ds_read_b128 v[150:153], v244 offset:17408
	ds_read_b128 v[154:157], v244 offset:18432
	ds_read_b128 v[158:161], v244 offset:19456
	s_add_u32 s4, s4, 0x160080
	s_addc_u32 s5, s5, 0
	ds_read_b128 v[178:181], v194
	ds_read_b128 v[182:185], v194 offset:1024
	ds_read_b128 v[186:189], v194 offset:2048
	ds_read_b128 v[196:199], v194 offset:3072
	ds_read_b128 v[200:203], v194 offset:4096
	ds_read_b128 v[204:207], v194 offset:5120
	ds_read_b128 v[208:211], v194 offset:6144
	ds_read_b128 v[212:215], v194 offset:7168
	s_add_i32 m0, s16, 0xc000
	s_nop 0
	global_load_lds_dwordx4 v1, s[4:5] sc0
	s_add_i32 m0, s16, 0xe000
	s_nop 0
	global_load_lds_dwordx4 v164, s[4:5] sc0
	s_waitcnt vmcnt(8)
	s_waitcnt lgkmcnt(0)
	s_barrier
	s_setprio 1
	s_waitcnt lgkmcnt(0)
	v_mfma_f32_16x16x32_bf16 v[142:145], v[34:37], v[178:181], v[142:145]
	v_mfma_f32_16x16x32_bf16 v[142:145], v[38:41], v[182:185], v[142:145]
	v_mfma_f32_16x16x32_bf16 v[134:137], v[34:37], v[186:189], v[134:137]
	v_mfma_f32_16x16x32_bf16 v[134:137], v[38:41], v[196:199], v[134:137]
	v_mfma_f32_16x16x32_bf16 v[126:129], v[34:37], v[200:203], v[126:129]
	v_mfma_f32_16x16x32_bf16 v[126:129], v[38:41], v[204:207], v[126:129]
	v_mfma_f32_16x16x32_bf16 v[118:121], v[34:37], v[208:211], v[118:121]
	v_mfma_f32_16x16x32_bf16 v[118:121], v[38:41], v[212:215], v[118:121]
	v_mfma_f32_16x16x32_bf16 v[138:141], v[98:101], v[178:181], v[138:141]
	v_mfma_f32_16x16x32_bf16 v[138:141], v[102:105], v[182:185], v[138:141]
	v_mfma_f32_16x16x32_bf16 v[130:133], v[98:101], v[186:189], v[130:133]
	v_mfma_f32_16x16x32_bf16 v[130:133], v[102:105], v[196:199], v[130:133]
	v_mfma_f32_16x16x32_bf16 v[122:125], v[98:101], v[200:203], v[122:125]
	v_mfma_f32_16x16x32_bf16 v[122:125], v[102:105], v[204:207], v[122:125]
	v_mfma_f32_16x16x32_bf16 v[114:117], v[98:101], v[208:211], v[114:117]
	v_mfma_f32_16x16x32_bf16 v[114:117], v[102:105], v[212:215], v[114:117]
	s_setprio 0
	s_setprio 1
	v_mfma_f32_16x16x32_bf16 v[70:73], v[146:149], v[178:181], v[70:73]
	v_mfma_f32_16x16x32_bf16 v[70:73], v[150:153], v[182:185], v[70:73]
	v_mfma_f32_16x16x32_bf16 v[62:65], v[146:149], v[186:189], v[62:65]
	v_mfma_f32_16x16x32_bf16 v[62:65], v[150:153], v[196:199], v[62:65]
	v_mfma_f32_16x16x32_bf16 v[54:57], v[146:149], v[200:203], v[54:57]
	v_mfma_f32_16x16x32_bf16 v[54:57], v[150:153], v[204:207], v[54:57]
	v_mfma_f32_16x16x32_bf16 v[46:49], v[146:149], v[208:211], v[46:49]
	v_mfma_f32_16x16x32_bf16 v[46:49], v[150:153], v[212:215], v[46:49]
	v_mfma_f32_16x16x32_bf16 v[66:69], v[154:157], v[178:181], v[66:69]
	v_mfma_f32_16x16x32_bf16 v[66:69], v[158:161], v[182:185], v[66:69]
	v_mfma_f32_16x16x32_bf16 v[58:61], v[154:157], v[186:189], v[58:61]
	v_mfma_f32_16x16x32_bf16 v[58:61], v[158:161], v[196:199], v[58:61]
	v_mfma_f32_16x16x32_bf16 v[50:53], v[154:157], v[200:203], v[50:53]
	v_mfma_f32_16x16x32_bf16 v[50:53], v[158:161], v[204:207], v[50:53]
	v_mfma_f32_16x16x32_bf16 v[42:45], v[154:157], v[208:211], v[42:45]
	v_mfma_f32_16x16x32_bf16 v[42:45], v[158:161], v[212:215], v[42:45]
	s_setprio 0
	s_barrier
	s_mov_b64 s[4:5], s[8:9]
	s_add_i32 s38, s38, s15
	ds_read_b128 v[178:181], v194 offset:16384
	ds_read_b128 v[182:185], v194 offset:17408
	ds_read_b128 v[186:189], v194 offset:18432
	ds_read_b128 v[196:199], v194 offset:19456
	ds_read_b128 v[200:203], v194 offset:20480
	ds_read_b128 v[204:207], v194 offset:21504
	ds_read_b128 v[208:211], v194 offset:22528
	ds_read_b128 v[212:215], v194 offset:23552
	s_mov_b32 m0, s38
	s_nop 0
	global_load_lds_dwordx4 v162, s[4:5] sc0
	s_add_i32 m0, s38, 0x2000
	s_nop 0
	global_load_lds_dwordx4 v190, s[4:5] sc0
	s_add_u32 s4, s8, 0x160000
	s_addc_u32 s5, s9, 0
	s_add_i32 s38, s39, s15
	s_mov_b32 m0, s38
	s_nop 0
	global_load_lds_dwordx4 v162, s[4:5] sc0
	s_add_i32 m0, s38, 0x2000
	s_nop 0
	global_load_lds_dwordx4 v190, s[4:5] sc0
	s_mov_b64 s[4:5], s[10:11]
	s_mov_b32 m0, s16
	s_nop 0
	global_load_lds_dwordx4 v1, s[4:5] sc0
	s_mov_b32 m0, s17
	s_nop 0
	global_load_lds_dwordx4 v164, s[4:5] sc0
	s_waitcnt vmcnt(8)
	s_waitcnt lgkmcnt(0)
	s_barrier
; #define PG8_STAGE(bufoff, gbase, voff) do { const char* gb_ = (const char*)(gbase); asm volatile("" : "+s"(gb_)); _Pragma("unroll") for (int _i = 0; _i < 2; ++_i) { unsigned vo_ = (voff)[_i]; asm volatile("" : "+v"(vo_));        \
;         __builtin_amdgcn_global_load_lds((const unsigned*)(gb_ + vo_), (PG8_LAS unsigned*)(lds + (bufoff) + ldsw + _i * 8192), 16, 0, 0); } } while (0)
; #define PG8_LDA(dst, b, h) do { _Pragma("unroll") for (int m = 0; m < 4; ++m) _Pragma("unroll") for (int k = 0; k < 2; ++k) dst[m][k] = *(const PG8_LAS bf16x8*)(lds + PG8_SA(b, h) + aoff + m * 2048 + k * 1024); } while (0)
; #define PG8_LDB(dst, b, h) do { _Pragma("unroll") for (int n = 0; n < 2; ++n) _Pragma("unroll") for (int k = 0; k < 2; ++k) dst[n][k] = *(const PG8_LAS bf16x8*)(lds + PG8_SB(b, h) + boff + n * 2048 + k * 1024); } while (0)
; #define PG8_WAIT_V(n) asm volatile("s_waitcnt vmcnt(" #n ")" ::: "memory")
; #define PG8_WAIT_L(n) asm volatile("s_waitcnt lgkmcnt(" #n ")" ::: "memory")
; #define PG8_BAR __builtin_amdgcn_s_barrier()
; #define PG8_SCHED __builtin_amdgcn_sched_barrier(0)
; template <class Epi, class Sched, bool ALIGN_EPI = false, bool SP2 = false>
; __device__ __forceinline__ void gemm_phase(PG8_LAS unsigned char* lds, const Gemm g, const Sched& S, const Epi& E) {
;     ...
;             PG8_LDB(B0, 0, 0); PG8_LDB(B1, 0, 1); PG8_SCHED; PG8_LDA(At, 0, 0); PG8_STAGE(PG8_SA(1, 1), a1 + hstep, voffA);
;             PG8_WAIT_V(8); PG8_WAIT_L(0); PG8_BAR; PG8_MMA(0, 0, At, B0); PG8_MMA(0, 1, At, B1); PG8_BAR; PG8_SCHED;
;             PG8_LDA(At, 0, 1); PG8_STAGE(PG8_SB(0, 0), b2, voffB); PG8_STAGE(PG8_SB(0, 1), b2 + hstep, voffB); PG8_STAGE(PG8_SA(0, 0), a2, voffA);
;             PG8_WAIT_V(8); PG8_WAIT_L(0); PG8_BAR; PG8_MMA(1, 0, At, B0); PG8_MMA(1, 1, At, B1); PG8_BAR; PG8_SCHED;
;             PG8_LDB(B0, 1, 0); PG8_LDB(B1, 1, 1); PG8_SCHED; PG8_LDA(At, 1, 0); PG8_STAGE(PG8_SA(0, 1), a2 + hstep, voffA);
;             PG8_WAIT_V(8); PG8_WAIT_L(0); PG8_BAR; PG8_MMA(0, 0, At, B0); PG8_MMA(0, 1, At, B1); PG8_BAR; PG8_SCHED;
;             PG8_LDA(At, 1, 1); PG8_STAGE(PG8_SB(1, 0), b3, voffB); PG8_STAGE(PG8_SB(1, 1), b3 + hstep, voffB); PG8_STAGE(PG8_SA(1, 0), a3, voffA);
;             PG8_WAIT_V(8); PG8_WAIT_L(0); PG8_BAR; PG8_MMA(1, 0, At, B0); PG8_MMA(1, 1, At, B1); PG8_BAR; PG8_SCHED;
	s_setprio 1
	s_waitcnt lgkmcnt(0)
	v_mfma_f32_16x16x32_bf16 v[110:113], v[34:37], v[178:181], v[110:113]
	v_mfma_f32_16x16x32_bf16 v[110:113], v[38:41], v[182:185], v[110:113]
	v_mfma_f32_16x16x32_bf16 v[94:97], v[34:37], v[186:189], v[94:97]
	v_mfma_f32_16x16x32_bf16 v[94:97], v[38:41], v[196:199], v[94:97]
	v_mfma_f32_16x16x32_bf16 v[86:89], v[34:37], v[200:203], v[86:89]
	v_mfma_f32_16x16x32_bf16 v[86:89], v[38:41], v[204:207], v[86:89]
	v_mfma_f32_16x16x32_bf16 v[34:37], v[34:37], v[208:211], v[78:81]
	v_mfma_f32_16x16x32_bf16 v[34:37], v[38:41], v[212:215], v[34:37]
	v_mfma_f32_16x16x32_bf16 v[106:109], v[98:101], v[178:181], v[106:109]
	v_mfma_f32_16x16x32_bf16 v[106:109], v[102:105], v[182:185], v[106:109]
	v_mfma_f32_16x16x32_bf16 v[90:93], v[98:101], v[186:189], v[90:93]
	v_mfma_f32_16x16x32_bf16 v[90:93], v[102:105], v[196:199], v[90:93]
	v_mfma_f32_16x16x32_bf16 v[82:85], v[98:101], v[200:203], v[82:85]
	v_mfma_f32_16x16x32_bf16 v[82:85], v[102:105], v[204:207], v[82:85]
	v_mfma_f32_16x16x32_bf16 v[38:41], v[98:101], v[208:211], v[74:77]
	v_mfma_f32_16x16x32_bf16 v[38:41], v[102:105], v[212:215], v[38:41]
	s_setprio 0
	s_setprio 1
	v_mfma_f32_16x16x32_bf16 v[30:33], v[146:149], v[178:181], v[30:33]
	v_mfma_f32_16x16x32_bf16 v[30:33], v[150:153], v[182:185], v[30:33]
	v_mfma_f32_16x16x32_bf16 v[22:25], v[146:149], v[186:189], v[22:25]
	v_mfma_f32_16x16x32_bf16 v[22:25], v[150:153], v[196:199], v[22:25]
	v_mfma_f32_16x16x32_bf16 v[14:17], v[146:149], v[200:203], v[14:17]
	v_mfma_f32_16x16x32_bf16 v[14:17], v[150:153], v[204:207], v[14:17]
	v_mfma_f32_16x16x32_bf16 v[6:9], v[146:149], v[208:211], v[6:9]
	v_mfma_f32_16x16x32_bf16 v[6:9], v[150:153], v[212:215], v[6:9]
	v_mfma_f32_16x16x32_bf16 v[26:29], v[154:157], v[178:181], v[26:29]
	v_mfma_f32_16x16x32_bf16 v[26:29], v[158:161], v[182:185], v[26:29]
	v_mfma_f32_16x16x32_bf16 v[18:21], v[154:157], v[186:189], v[18:21]
	v_mfma_f32_16x16x32_bf16 v[18:21], v[158:161], v[196:199], v[18:21]
	v_mfma_f32_16x16x32_bf16 v[10:13], v[154:157], v[200:203], v[10:13]
	v_mfma_f32_16x16x32_bf16 v[10:13], v[158:161], v[204:207], v[10:13]
	v_mfma_f32_16x16x32_bf16 v[2:5], v[154:157], v[208:211], v[2:5]
	v_mfma_f32_16x16x32_bf16 v[2:5], v[158:161], v[212:215], v[2:5]
	s_setprio 0
	s_barrier
	s_add_i32 s38, 0, 0x18000
	s_add_i32 s39, 0, 0x1c000
	ds_read_b128 v[74:77], v244 offset:32768
	ds_read_b128 v[78:81], v244 offset:33792
	ds_read_b128 v[98:101], v244 offset:34816
	ds_read_b128 v[102:105], v244 offset:35840
	ds_read_b128 v[146:149], v244 offset:49152
	ds_read_b128 v[150:153], v244 offset:50176
	ds_read_b128 v[154:157], v244 offset:51200
	ds_read_b128 v[158:161], v244 offset:52224
	s_add_u32 s4, s10, 0x160000
	s_addc_u32 s5, s11, 0
	s_mov_b32 m0, s18
	ds_read_b128 v[178:181], v194 offset:32768
	ds_read_b128 v[182:185], v194 offset:33792
	ds_read_b128 v[186:189], v194 offset:34816
	ds_read_b128 v[196:199], v194 offset:35840
	ds_read_b128 v[200:203], v194 offset:36864
	ds_read_b128 v[204:207], v194 offset:37888
	ds_read_b128 v[208:211], v194 offset:38912
	ds_read_b128 v[212:215], v194 offset:39936
	s_nop 0
	global_load_lds_dwordx4 v1, s[4:5] sc0
	s_mov_b32 m0, s19
	s_nop 0
	global_load_lds_dwordx4 v164, s[4:5] sc0
	s_waitcnt vmcnt(8)
	s_waitcnt lgkmcnt(0)
	s_barrier
	s_setprio 1
	s_waitcnt lgkmcnt(0)
	v_mfma_f32_16x16x32_bf16 v[142:145], v[74:77], v[178:181], v[142:145]
	v_mfma_f32_16x16x32_bf16 v[142:145], v[78:81], v[182:185], v[142:145]
	v_mfma_f32_16x16x32_bf16 v[134:137], v[74:77], v[186:189], v[134:137]
	v_mfma_f32_16x16x32_bf16 v[134:137], v[78:81], v[196:199], v[134:137]
	v_mfma_f32_16x16x32_bf16 v[126:129], v[74:77], v[200:203], v[126:129]
	v_mfma_f32_16x16x32_bf16 v[126:129], v[78:81], v[204:207], v[126:129]
	v_mfma_f32_16x16x32_bf16 v[118:121], v[74:77], v[208:211], v[118:121]
	v_mfma_f32_16x16x32_bf16 v[118:121], v[78:81], v[212:215], v[118:121]
	v_mfma_f32_16x16x32_bf16 v[138:141], v[98:101], v[178:181], v[138:141]
	v_mfma_f32_16x16x32_bf16 v[138:141], v[102:105], v[182:185], v[138:141]
	v_mfma_f32_16x16x32_bf16 v[130:133], v[98:101], v[186:189], v[130:133]
	v_mfma_f32_16x16x32_bf16 v[130:133], v[102:105], v[196:199], v[130:133]
	v_mfma_f32_16x16x32_bf16 v[122:125], v[98:101], v[200:203], v[122:125]
	v_mfma_f32_16x16x32_bf16 v[122:125], v[102:105], v[204:207], v[122:125]
	v_mfma_f32_16x16x32_bf16 v[114:117], v[98:101], v[208:211], v[114:117]
	v_mfma_f32_16x16x32_bf16 v[114:117], v[102:105], v[212:215], v[114:117]
	s_setprio 0
	s_setprio 1
	v_mfma_f32_16x16x32_bf16 v[70:73], v[146:149], v[178:181], v[70:73]
	v_mfma_f32_16x16x32_bf16 v[70:73], v[150:153], v[182:185], v[70:73]
	v_mfma_f32_16x16x32_bf16 v[62:65], v[146:149], v[186:189], v[62:65]
	v_mfma_f32_16x16x32_bf16 v[62:65], v[150:153], v[196:199], v[62:65]
	v_mfma_f32_16x16x32_bf16 v[54:57], v[146:149], v[200:203], v[54:57]
	v_mfma_f32_16x16x32_bf16 v[54:57], v[150:153], v[204:207], v[54:57]
	v_mfma_f32_16x16x32_bf16 v[46:49], v[146:149], v[208:211], v[46:49]
	v_mfma_f32_16x16x32_bf16 v[46:49], v[150:153], v[212:215], v[46:49]
	v_mfma_f32_16x16x32_bf16 v[66:69], v[154:157], v[178:181], v[66:69]
	v_mfma_f32_16x16x32_bf16 v[66:69], v[158:161], v[182:185], v[66:69]
	v_mfma_f32_16x16x32_bf16 v[58:61], v[154:157], v[186:189], v[58:61]
	v_mfma_f32_16x16x32_bf16 v[58:61], v[158:161], v[196:199], v[58:61]
	v_mfma_f32_16x16x32_bf16 v[50:53], v[154:157], v[200:203], v[50:53]
	v_mfma_f32_16x16x32_bf16 v[50:53], v[158:161], v[204:207], v[50:53]
	v_mfma_f32_16x16x32_bf16 v[42:45], v[154:157], v[208:211], v[42:45]
	v_mfma_f32_16x16x32_bf16 v[42:45], v[158:161], v[212:215], v[42:45]
	s_setprio 0
	s_barrier
; #define PG8_STAGE(bufoff, gbase, voff) do { const char* gb_ = (const char*)(gbase); asm volatile("" : "+s"(gb_)); _Pragma("unroll") for (int _i = 0; _i < 2; ++_i) { unsigned vo_ = (voff)[_i]; asm volatile("" : "+v"(vo_));        \
;         __builtin_amdgcn_global_load_lds((const unsigned*)(gb_ + vo_), (PG8_LAS unsigned*)(lds + (bufoff) + ldsw + _i * 8192), 16, 0, 0); } } while (0)
; #define PG8_LDA(dst, b, h) do { _Pragma("unroll") for (int m = 0; m < 4; ++m) _Pragma("unroll") for (int k = 0; k < 2; ++k) dst[m][k] = *(const PG8_LAS bf16x8*)(lds + PG8_SA(b, h) + aoff + m * 2048 + k * 1024); } while (0)
; #define PG8_WAIT_V(n) asm volatile("s_waitcnt vmcnt(" #n ")" ::: "memory")
; #define PG8_WAIT_L(n) asm volatile("s_waitcnt lgkmcnt(" #n ")" ::: "memory")
; #define PG8_BAR __builtin_amdgcn_s_barrier()
; #define PG8_SCHED __builtin_amdgcn_sched_barrier(0)
;     __device__ __forceinline__ void operator()(const f32x4 (&acc)[2][2][4][2], const Unit& u, int wr, int wc, int fr, int fq) const {
;         const int row0 = u.pm * BM + wr * 64 + fr, col0 = u.pn * BM + wc * 32 + 8 * fq, b = (u.pm * BM) / rows_per_batch;
;         const float* g = gate + (size_t)b * gate_bstride + col0;
;         float ssq[2][4];
; #pragma unroll
;         for (int ai = 0; ai < 2; ++ai)
; #pragma unroll
;             for (int m = 0; m < 4; ++m) ssq[ai][m] = 0.f;
;         f32x4 gv[2][2], Gv[2][2];
; #pragma unroll
;         for (int bj = 0; bj < 2; ++bj) { gv[bj][0] = *(const f32x4*)(g + bj * HALF); gv[bj][1] = *(const f32x4*)(g + bj * HALF + 4); Gv[bj][0] = (f32x4){0.f, 0.f, 0.f, 0.f}; Gv[bj][1] = (f32x4){0.f, 0.f, 0.f, 0.f};
;             if (Hn) { const float* sc = scnext + (size_t)b * gate_bstride + col0 + bj * HALF;
;                 Gv[bj][0] = *(const f32x4*)(gnext + col0 + bj * HALF) * (1.0f + *(const f32x4*)(sc)); Gv[bj][1] = *(const f32x4*)(gnext + col0 + bj * HALF + 4) * (1.0f + *(const f32x4*)(sc + 4)); } }
; template <class Epi, class Sched, bool ALIGN_EPI = false, bool SP2 = false>
; __device__ __forceinline__ void gemm_phase(PG8_LAS unsigned char* lds, const Gemm g, const Sched& S, const Epi& E) {
;     ...
;             PG8_LDA(At, 1, 1); PG8_STAGE(PG8_SB(1, 0), b3, voffB); PG8_STAGE(PG8_SB(1, 1), b3 + hstep, voffB); PG8_STAGE(PG8_SA(1, 0), a3, voffA);
;             PG8_WAIT_V(8); PG8_WAIT_L(0); PG8_BAR; PG8_MMA(1, 0, At, B0); PG8_MMA(1, 1, At, B1); PG8_BAR; PG8_SCHED;
	s_add_u32 s4, s8, 0x80
	s_addc_u32 s5, s9, 0
	s_add_i32 s10, s38, s15
	ds_read_b128 v[178:181], v194 offset:49152
	ds_read_b128 v[182:185], v194 offset:50176
	ds_read_b128 v[186:189], v194 offset:51200
	ds_read_b128 v[196:199], v194 offset:52224
	ds_read_b128 v[200:203], v194 offset:53248
	ds_read_b128 v[204:207], v194 offset:54272
	ds_read_b128 v[208:211], v194 offset:55296
	ds_read_b128 v[212:215], v194 offset:56320
	s_mov_b32 m0, s10
	s_nop 0
	global_load_lds_dwordx4 v162, s[4:5] sc0
	s_add_i32 m0, s10, 0x2000
	s_nop 0
	global_load_lds_dwordx4 v190, s[4:5] sc0
	s_add_u32 s4, s8, 0x160080
	s_addc_u32 s5, s9, 0
	s_add_i32 s8, s39, s15
	s_mov_b32 m0, s8
	s_nop 0
	global_load_lds_dwordx4 v162, s[4:5] sc0
	s_add_i32 m0, s8, 0x2000
	s_nop 0
	global_load_lds_dwordx4 v190, s[4:5] sc0
	s_mov_b32 m0, s24
	s_nop 0
	global_load_lds_dwordx4 v1, s[6:7] sc0
	s_mov_b32 m0, s25
	s_nop 0
	global_load_lds_dwordx4 v164, s[6:7] sc0
	s_waitcnt vmcnt(8)
	s_waitcnt lgkmcnt(0)
	s_barrier
	s_setprio 1
	s_waitcnt lgkmcnt(0)
	v_mfma_f32_16x16x32_bf16 v[110:113], v[74:77], v[178:181], v[110:113]
	v_mfma_f32_16x16x32_bf16 v[110:113], v[78:81], v[182:185], v[110:113]
	v_mfma_f32_16x16x32_bf16 v[94:97], v[74:77], v[186:189], v[94:97]
	v_mfma_f32_16x16x32_bf16 v[94:97], v[78:81], v[196:199], v[94:97]
	v_mfma_f32_16x16x32_bf16 v[86:89], v[74:77], v[200:203], v[86:89]
	v_mfma_f32_16x16x32_bf16 v[86:89], v[78:81], v[204:207], v[86:89]
	v_mfma_f32_16x16x32_bf16 v[34:37], v[74:77], v[208:211], v[34:37]
	v_mfma_f32_16x16x32_bf16 v[78:81], v[78:81], v[212:215], v[34:37]
	v_mfma_f32_16x16x32_bf16 v[106:109], v[98:101], v[178:181], v[106:109]
	v_mfma_f32_16x16x32_bf16 v[106:109], v[102:105], v[182:185], v[106:109]
	v_mfma_f32_16x16x32_bf16 v[90:93], v[98:101], v[186:189], v[90:93]
	v_mfma_f32_16x16x32_bf16 v[90:93], v[102:105], v[196:199], v[90:93]
	v_mfma_f32_16x16x32_bf16 v[82:85], v[98:101], v[200:203], v[82:85]
	v_mfma_f32_16x16x32_bf16 v[82:85], v[102:105], v[204:207], v[82:85]
	v_mfma_f32_16x16x32_bf16 v[34:37], v[98:101], v[208:211], v[38:41]
	v_mfma_f32_16x16x32_bf16 v[74:77], v[102:105], v[212:215], v[34:37]
	s_setprio 0
	s_setprio 1
	v_mfma_f32_16x16x32_bf16 v[30:33], v[146:149], v[178:181], v[30:33]
	v_mfma_f32_16x16x32_bf16 v[30:33], v[150:153], v[182:185], v[30:33]
	v_mfma_f32_16x16x32_bf16 v[22:25], v[146:149], v[186:189], v[22:25]
	v_mfma_f32_16x16x32_bf16 v[22:25], v[150:153], v[196:199], v[22:25]
	v_mfma_f32_16x16x32_bf16 v[14:17], v[146:149], v[200:203], v[14:17]
	v_mfma_f32_16x16x32_bf16 v[14:17], v[150:153], v[204:207], v[14:17]
	v_mfma_f32_16x16x32_bf16 v[6:9], v[146:149], v[208:211], v[6:9]
	v_mfma_f32_16x16x32_bf16 v[6:9], v[150:153], v[212:215], v[6:9]
	v_mfma_f32_16x16x32_bf16 v[26:29], v[154:157], v[178:181], v[26:29]
	v_mfma_f32_16x16x32_bf16 v[26:29], v[158:161], v[182:185], v[26:29]
	v_mfma_f32_16x16x32_bf16 v[18:21], v[154:157], v[186:189], v[18:21]
	v_mfma_f32_16x16x32_bf16 v[18:21], v[158:161], v[196:199], v[18:21]
	v_mfma_f32_16x16x32_bf16 v[10:13], v[154:157], v[200:203], v[10:13]
	v_mfma_f32_16x16x32_bf16 v[10:13], v[158:161], v[204:207], v[10:13]
	v_mfma_f32_16x16x32_bf16 v[2:5], v[154:157], v[208:211], v[2:5]
	v_mfma_f32_16x16x32_bf16 v[2:5], v[158:161], v[212:215], v[2:5]
	s_setprio 0
	s_barrier
	s_add_i32 s35, s35, 2
	s_add_u32 s31, s31, 0x100
	s_addc_u32 s34, s34, 0
	s_cmpk_gt_u32 s35, 0x55
	s_mov_b64 s[4:5], s[2:3]
	s_cbranch_scc0 .LBB0_707
	s_ashr_i32 s2, s29, 31
	s_lshr_b32 s2, s2, 27
	s_add_i32 s2, s29, s2
	s_ashr_i32 s2, s2, 5
	v_lshl_or_b32 v156, s30, 8, v193
	s_mul_i32 s5, s2, 0xc000
	v_ashrrev_i32_e32 v157, 31, v156
	s_mul_hi_i32 s4, s2, 0xc000
	s_add_u32 s2, s20, s5
	s_addc_u32 s3, s21, s4
	v_lshlrev_b64 v[34:35], 2, v[156:157]
	v_lshl_add_u64 v[38:39], s[2:3], 0, v[34:35]
	global_load_dwordx4 v[98:101], v[38:39], off offset:16
	global_load_dwordx4 v[102:105], v[38:39], off
	s_add_u32 s2, s22, s5
	s_addc_u32 s3, s23, s4
	v_lshl_add_u64 v[148:149], s[2:3], 0, v[34:35]
	v_lshl_add_u64 v[146:147], s[48:49], 0, v[34:35]
	v_mov_b32_e32 v158, 0
	v_cndmask_b32_e64 v34, 0, 1, s[46:47]
	v_cmp_ne_u32_e64 s[2:3], 1, v34
	s_andn2_b64 vcc, exec, s[46:47]
	v_mov_b32_e32 v159, v158
	v_mov_b32_e32 v160, v158
	v_mov_b32_e32 v161, v158
	v_mov_b32_e32 v178, v158
	v_mov_b32_e32 v179, v158
	v_mov_b32_e32 v180, v158
	v_mov_b32_e32 v181, v158
	s_cbranch_vccnz .LBB0_710
	global_load_dwordx4 v[34:37], v[148:149], off
	global_load_dwordx4 v[150:153], v[148:149], off offset:16
	global_load_dwordx4 v[158:161], v[146:147], off
	global_load_dwordx4 v[178:181], v[146:147], off offset:16
	s_waitcnt vmcnt(0)
	v_pk_add_f32 v[36:37], v[36:37], 1.0 op_sel_hi:[1,0]
	v_pk_add_f32 v[34:35], v[34:35], 1.0 op_sel_hi:[1,0]
	v_pk_add_f32 v[40:41], v[152:153], 1.0 op_sel_hi:[1,0]
	v_pk_add_f32 v[150:151], v[150:151], 1.0 op_sel_hi:[1,0]
	v_pk_mul_f32 v[160:161], v[160:161], v[36:37]
	v_pk_mul_f32 v[158:159], v[158:159], v[34:35]
	v_pk_mul_f32 v[180:181], v[180:181], v[40:41]
	v_pk_mul_f32 v[178:179], v[178:179], v[150:151]
